# cache policy: write-through (sc1) stores for the large phase outputs (H, PROJ, ACT, MERGED, out, converted weights), nt on read-once streams (x rows in rmsnorm, residual rows, f32 weights)
# speedup vs baseline: 1.2674x; 1.0154x over previous
;     ...
; #pragma unroll 1
;     for (int kt = 0; kt < nk - 1; ++kt) {
;       asm volatile("s_waitcnt vmcnt(0) lgkmcnt(0)" ::: "memory");
;       __builtin_amdgcn_s_barrier();
;       asm volatile("" ::: "memory");
;       G3_STEP(kt, true)
;     }
.LBB0_37:
	s_lshl_b32 s11, s9, 1
	s_and_b32 s11, s11, 0x8000
	v_lshl_or_b32 v87, v86, 1, s11
	s_waitcnt vmcnt(0) lgkmcnt(0)
	s_barrier
	v_add3_u32 v100, v87, v84, v83
	v_add3_u32 v87, v87, v82, v83
	ds_read_b128 v[88:91], v100
	ds_read_b128 v[92:95], v100 offset:2048
	ds_read_b128 v[96:99], v100 offset:4096
	ds_read_b128 v[100:103], v100 offset:6144
	ds_read_b128 v[104:107], v87 offset:16384
	ds_read_b128 v[108:111], v87 offset:18432
	ds_read_b128 v[112:115], v87 offset:20480
	ds_read_b128 v[116:119], v87 offset:22528
	v_lshl_or_b32 v87, v85, 1, s11
	v_add3_u32 v132, v87, v84, v83
	v_add3_u32 v87, v87, v82, v83
	ds_read_b128 v[120:123], v132
	ds_read_b128 v[124:127], v132 offset:2048
	ds_read_b128 v[128:131], v132 offset:4096
	ds_read_b128 v[132:135], v132 offset:6144
	ds_read_b128 v[136:139], v87 offset:16384
	ds_read_b128 v[140:143], v87 offset:18432
	ds_read_b128 v[144:147], v87 offset:20480
	ds_read_b128 v[148:151], v87 offset:22528
	s_setprio 1
	s_andn2_b32 s11, 0x8000, s10
	s_waitcnt lgkmcnt(11)
	v_mfma_f32_16x16x32_bf16 v[60:63], v[88:91], v[104:107], v[60:63]
	s_add_i32 s11, s8, s11
	v_lshl_add_u64 v[172:173], v[64:65], 0, s[0:1]
	s_mov_b32 m0, s11
	s_nop 0
	global_load_lds_dwordx4 v[172:173], off
	s_waitcnt lgkmcnt(10)
	v_mfma_f32_16x16x32_bf16 v[56:59], v[88:91], v[108:111], v[56:59]
	v_lshl_add_u64 v[152:153], v[78:79], 0, s[0:1]
	v_lshl_add_u64 v[154:155], v[76:77], 0, s[0:1]
	v_lshl_add_u64 v[156:157], v[74:75], 0, s[0:1]
	v_lshl_add_u64 v[158:159], v[72:73], 0, s[0:1]
	v_lshl_add_u64 v[166:167], v[70:71], 0, s[0:1]
	v_lshl_add_u64 v[168:169], v[68:69], 0, s[0:1]
	v_lshl_add_u64 v[170:171], v[66:67], 0, s[0:1]
	s_waitcnt lgkmcnt(9)
	v_mfma_f32_16x16x32_bf16 v[52:55], v[88:91], v[112:115], v[52:55]
	s_add_i32 s12, s11, 0x400
	s_mov_b32 m0, s12
	s_nop 0
	global_load_lds_dwordx4 v[168:169], off
	s_waitcnt lgkmcnt(8)
	v_mfma_f32_16x16x32_bf16 v[48:51], v[88:91], v[116:119], v[48:51]
	v_mfma_f32_16x16x32_bf16 v[44:47], v[92:95], v[104:107], v[44:47]
	s_add_i32 s12, s11, 0x800
	s_mov_b32 m0, s12
	s_nop 0
	global_load_lds_dwordx4 v[156:157], off
	v_mfma_f32_16x16x32_bf16 v[40:43], v[92:95], v[108:111], v[40:43]
	v_mfma_f32_16x16x32_bf16 v[36:39], v[92:95], v[112:115], v[36:39]
	s_add_i32 s12, s11, 0xc00
	s_mov_b32 m0, s12
	s_nop 0
	global_load_lds_dwordx4 v[166:167], off
	v_mfma_f32_16x16x32_bf16 v[32:35], v[92:95], v[116:119], v[32:35]
	v_mfma_f32_16x16x32_bf16 v[28:31], v[96:99], v[104:107], v[28:31]
	s_add_i32 s12, s11, 0x4000
	s_mov_b32 m0, s12
	s_nop 0
	global_load_lds_dwordx4 v[154:155], off
	v_mfma_f32_16x16x32_bf16 v[24:27], v[96:99], v[108:111], v[24:27]
	v_mfma_f32_16x16x32_bf16 v[20:23], v[96:99], v[112:115], v[20:23]
	s_add_i32 s12, s11, 0x4400
	s_mov_b32 m0, s12
	s_nop 0
	global_load_lds_dwordx4 v[158:159], off
	v_mfma_f32_16x16x32_bf16 v[16:19], v[96:99], v[116:119], v[16:19]
	v_mfma_f32_16x16x32_bf16 v[12:15], v[100:103], v[104:107], v[12:15]
	s_add_i32 s12, s11, 0x4800
	s_mov_b32 m0, s12
	s_nop 0
	global_load_lds_dwordx4 v[152:153], off
	v_mfma_f32_16x16x32_bf16 v[8:11], v[100:103], v[108:111], v[8:11]
	v_mfma_f32_16x16x32_bf16 v[4:7], v[100:103], v[112:115], v[4:7]
	s_addk_i32 s11, 0x4c00
	s_mov_b32 m0, s11
	s_nop 0
	global_load_lds_dwordx4 v[170:171], off
	v_mfma_f32_16x16x32_bf16 v[0:3], v[100:103], v[116:119], v[0:3]
	s_waitcnt lgkmcnt(3)
	v_mfma_f32_16x16x32_bf16 v[60:63], v[120:123], v[136:139], v[60:63]
	s_waitcnt lgkmcnt(2)
	v_mfma_f32_16x16x32_bf16 v[56:59], v[120:123], v[140:143], v[56:59]
	s_waitcnt lgkmcnt(1)
	v_mfma_f32_16x16x32_bf16 v[52:55], v[120:123], v[144:147], v[52:55]
	s_waitcnt lgkmcnt(0)
	v_mfma_f32_16x16x32_bf16 v[48:51], v[120:123], v[148:151], v[48:51]
	v_mfma_f32_16x16x32_bf16 v[44:47], v[124:127], v[136:139], v[44:47]
	v_mfma_f32_16x16x32_bf16 v[40:43], v[124:127], v[140:143], v[40:43]
	v_mfma_f32_16x16x32_bf16 v[36:39], v[124:127], v[144:147], v[36:39]
	v_mfma_f32_16x16x32_bf16 v[32:35], v[124:127], v[148:151], v[32:35]
	v_mfma_f32_16x16x32_bf16 v[28:31], v[128:131], v[136:139], v[28:31]
	v_mfma_f32_16x16x32_bf16 v[24:27], v[128:131], v[140:143], v[24:27]
	v_mfma_f32_16x16x32_bf16 v[20:23], v[128:131], v[144:147], v[20:23]
	v_mfma_f32_16x16x32_bf16 v[16:19], v[128:131], v[148:151], v[16:19]
	v_mfma_f32_16x16x32_bf16 v[12:15], v[132:135], v[136:139], v[12:15]
	v_mfma_f32_16x16x32_bf16 v[8:11], v[132:135], v[140:143], v[8:11]
	v_mfma_f32_16x16x32_bf16 v[4:7], v[132:135], v[144:147], v[4:7]
	v_mfma_f32_16x16x32_bf16 v[0:3], v[132:135], v[148:151], v[0:3]
	s_setprio 0
	s_add_i32 s10, s10, 0x8000
	s_add_u32 s0, s0, 0x80
	s_addc_u32 s1, s1, 0
	s_addk_i32 s9, 0x4000
	s_cmpk_lg_i32 s0, 0x1580
	s_cbranch_scc1 .LBB0_37
	v_lshlrev_b32_e32 v86, 1, v86
	v_lshlrev_b32_e32 v85, 1, v85
	s_waitcnt vmcnt(0) lgkmcnt(0)
	s_barrier
; DI void resid_tile(const u16* A, int K, const u16* Bt, const float* resid, float* out, int it, u16* sA, u16* sB) {
;     ...
;   float* sC = (float*)sA + w * (32 * 68);
; #pragma unroll
;   for (int hp = 0; hp < 2; ++hp) {
;     __syncthreads();
; #pragma unroll
;     for (int mi2 = 0; mi2 < 2; ++mi2)
; #pragma unroll
;       for (int ni = 0; ni < 4; ++ni)
; #pragma unroll
;         for (int j = 0; j < 4; ++j) sC[(16 * mi2 + 4 * quad + j) * 68 + 16 * ni + r16] = acc[2 * hp + mi2][ni][j];
;     __syncthreads();
; #pragma unroll
;     for (int q = 0; q < 8; ++q) {
;       const int c = lane + 64 * q, row = c >> 4, c4 = (c & 15) * 4;
;       const long o = ((long)mt * 128 + wm * 64 + 32 * hp + row) * DM + nt * 128 + wn * 64 + c4;
;       const float4 rv = *(const float4*)(resid + o);
	v_add3_u32 v76, v86, v84, v83
	v_add3_u32 v98, v86, v82, v83
	v_add3_u32 v84, v85, v84, v83
	v_add3_u32 v126, v85, v82, v83
	ds_read_b128 v[64:67], v76 offset:32768
	ds_read_b128 v[68:71], v76 offset:34816
	ds_read_b128 v[72:75], v76 offset:36864
	ds_read_b128 v[76:79], v76 offset:38912
	ds_read_b128 v[86:89], v98 offset:49152
	ds_read_b128 v[90:93], v98 offset:51200
	ds_read_b128 v[94:97], v98 offset:53248
	ds_read_b128 v[98:101], v98 offset:55296
	ds_read_b128 v[102:105], v84 offset:32768
	ds_read_b128 v[106:109], v84 offset:34816
	ds_read_b128 v[110:113], v84 offset:36864
	ds_read_b128 v[114:117], v84 offset:38912
	ds_read_b128 v[82:85], v126 offset:49152
	ds_read_b128 v[118:121], v126 offset:51200
	ds_read_b128 v[122:125], v126 offset:53248
	ds_read_b128 v[126:129], v126 offset:55296
	s_lshl_b64 s[0:1], s[2:3], 7
	v_and_b32_e32 v130, 15, v80
	s_setprio 1
	s_waitcnt lgkmcnt(11)
	v_mfma_f32_16x16x32_bf16 v[60:63], v[64:67], v[86:89], v[60:63]
	s_waitcnt lgkmcnt(10)
	v_mfma_f32_16x16x32_bf16 v[56:59], v[64:67], v[90:93], v[56:59]
	s_waitcnt lgkmcnt(9)
	v_mfma_f32_16x16x32_bf16 v[52:55], v[64:67], v[94:97], v[52:55]
	s_waitcnt lgkmcnt(8)
	v_mfma_f32_16x16x32_bf16 v[48:51], v[64:67], v[98:101], v[48:51]
	v_mfma_f32_16x16x32_bf16 v[44:47], v[68:71], v[86:89], v[44:47]
	v_mfma_f32_16x16x32_bf16 v[40:43], v[68:71], v[90:93], v[40:43]
	v_mfma_f32_16x16x32_bf16 v[36:39], v[68:71], v[94:97], v[36:39]
	v_mfma_f32_16x16x32_bf16 v[32:35], v[68:71], v[98:101], v[32:35]
	v_mfma_f32_16x16x32_bf16 v[28:31], v[72:75], v[86:89], v[28:31]
	v_mfma_f32_16x16x32_bf16 v[64:67], v[72:75], v[90:93], v[24:27]
	v_mfma_f32_16x16x32_bf16 v[20:23], v[72:75], v[94:97], v[20:23]
	v_mfma_f32_16x16x32_bf16 v[68:71], v[72:75], v[98:101], v[16:19]
	v_mfma_f32_16x16x32_bf16 v[12:15], v[76:79], v[86:89], v[12:15]
	v_mfma_f32_16x16x32_bf16 v[72:75], v[76:79], v[90:93], v[8:11]
	v_mfma_f32_16x16x32_bf16 v[4:7], v[76:79], v[94:97], v[4:7]
	v_mfma_f32_16x16x32_bf16 v[76:79], v[76:79], v[98:101], v[0:3]
	s_waitcnt lgkmcnt(3)
	v_mfma_f32_16x16x32_bf16 v[60:63], v[102:105], v[82:85], v[60:63]
	s_waitcnt lgkmcnt(2)
	v_mfma_f32_16x16x32_bf16 v[56:59], v[102:105], v[118:121], v[56:59]
	s_waitcnt lgkmcnt(1)
	v_mfma_f32_16x16x32_bf16 v[52:55], v[102:105], v[122:125], v[52:55]
	s_waitcnt lgkmcnt(0)
	v_mfma_f32_16x16x32_bf16 v[48:51], v[102:105], v[126:129], v[48:51]
	v_mfma_f32_16x16x32_bf16 v[44:47], v[106:109], v[82:85], v[44:47]
	v_mfma_f32_16x16x32_bf16 v[40:43], v[106:109], v[118:121], v[40:43]
	v_mfma_f32_16x16x32_bf16 v[36:39], v[106:109], v[122:125], v[36:39]
	v_mfma_f32_16x16x32_bf16 v[86:89], v[106:109], v[126:129], v[32:35]
	v_mfma_f32_16x16x32_bf16 v[24:27], v[110:113], v[82:85], v[28:31]
	v_mfma_f32_16x16x32_bf16 v[28:31], v[110:113], v[118:121], v[64:67]
	v_mfma_f32_16x16x32_bf16 v[16:19], v[110:113], v[122:125], v[20:23]
	v_mfma_f32_16x16x32_bf16 v[20:23], v[110:113], v[126:129], v[68:71]
	v_mfma_f32_16x16x32_bf16 v[8:11], v[114:117], v[82:85], v[12:15]
	v_mfma_f32_16x16x32_bf16 v[12:15], v[114:117], v[118:121], v[72:75]
	v_mfma_f32_16x16x32_bf16 v[0:3], v[114:117], v[122:125], v[4:7]
	v_mfma_f32_16x16x32_bf16 v[4:7], v[114:117], v[126:129], v[76:79]
	s_setprio 0
	v_lshrrev_b32_e32 v32, 2, v80
	v_and_b32_e32 v65, 12, v32
	v_lshlrev_b32_e32 v32, 2, v80
	v_and_b32_e32 v67, 60, v32
	v_ashrrev_i32_e32 v32, 1, v80
	v_and_b32_e32 v32, 0xffffffc0, v32
	v_ashrrev_i32_e32 v33, 31, v32
	v_mul_lo_u32 v64, v81, s18
	v_lshl_add_u64 v[32:33], s[0:1], 0, v[32:33]
	s_lshl_b32 s0, s7, 7
	v_and_b32_e32 v34, 64, v80
	v_lshl_or_b32 v66, v130, 2, v64
	s_ashr_i32 s1, s0, 31
	v_or3_b32 v34, s0, v34, v67
	s_movk_i32 s0, 0x110
	v_mad_u32_u24 v65, v65, s0, v66
	v_lshl_or_b32 v64, v67, 2, v64
	v_bfe_u32 v67, v80, 4, 2
	v_lshlrev_b32_e32 v175, 2, v34
	v_or3_b32 v174, v32, v67, 0
	v_lshl_add_u32 v90, v174, 12, v175
	global_load_dwordx4 v[106:109], v90, s[68:69] nt
	v_or3_b32 v174, v32, v67, 4
	v_lshl_add_u32 v91, v174, 12, v175
	global_load_dwordx4 v[110:113], v91, s[68:69] nt
	v_or3_b32 v174, v32, v67, 8
	v_lshl_add_u32 v92, v174, 12, v175
	global_load_dwordx4 v[114:117], v92, s[68:69] nt
	v_or3_b32 v174, v32, v67, 12
	v_lshl_add_u32 v93, v174, 12, v175
	global_load_dwordx4 v[118:121], v93, s[68:69] nt
	v_or3_b32 v174, v32, v67, 16
	v_lshl_add_u32 v94, v174, 12, v175
	global_load_dwordx4 v[122:125], v94, s[68:69] nt
	v_or3_b32 v174, v32, v67, 20
	v_lshl_add_u32 v95, v174, 12, v175
	global_load_dwordx4 v[126:129], v95, s[68:69] nt
	v_or3_b32 v174, v32, v67, 24
	v_lshl_add_u32 v96, v174, 12, v175
	global_load_dwordx4 v[130:133], v96, s[68:69] nt
	v_or3_b32 v174, v32, v67, 28
	v_lshl_add_u32 v97, v174, 12, v175
	global_load_dwordx4 v[134:137], v97, s[68:69] nt
	v_or3_b32 v174, v32, v67, 32
	v_lshl_add_u32 v98, v174, 12, v175
	global_load_dwordx4 v[210:213], v98, s[68:69] nt
	v_or3_b32 v174, v32, v67, 36
	v_lshl_add_u32 v99, v174, 12, v175
	global_load_dwordx4 v[214:217], v99, s[68:69] nt
	v_or3_b32 v174, v32, v67, 40
	v_lshl_add_u32 v100, v174, 12, v175
	global_load_dwordx4 v[218:221], v100, s[68:69] nt
	v_or3_b32 v174, v32, v67, 44
	v_lshl_add_u32 v101, v174, 12, v175
	global_load_dwordx4 v[222:225], v101, s[68:69] nt
	v_or3_b32 v174, v32, v67, 48
	v_lshl_add_u32 v102, v174, 12, v175
	global_load_dwordx4 v[226:229], v102, s[68:69] nt
	v_or3_b32 v174, v32, v67, 52
	v_lshl_add_u32 v103, v174, 12, v175
	global_load_dwordx4 v[230:233], v103, s[68:69] nt
	v_or3_b32 v174, v32, v67, 56
	v_lshl_add_u32 v104, v174, 12, v175
	global_load_dwordx4 v[234:237], v104, s[68:69] nt
	v_or3_b32 v174, v32, v67, 60
	v_lshl_add_u32 v105, v174, 12, v175
	global_load_dwordx4 v[238:241], v105, s[68:69] nt
	s_barrier
; DI void resid_tile(const u16* A, int K, const u16* Bt, const float* resid, float* out, int it, u16* sA, u16* sB) {
;     ...
;   for (int hp = 0; hp < 2; ++hp) {
;     __syncthreads();
; #pragma unroll
;     for (int mi2 = 0; mi2 < 2; ++mi2)
; #pragma unroll
;       for (int ni = 0; ni < 4; ++ni)
; #pragma unroll
;         for (int j = 0; j < 4; ++j) sC[(16 * mi2 + 4 * quad + j) * 68 + 16 * ni + r16] = acc[2 * hp + mi2][ni][j];
;     __syncthreads();
; #pragma unroll
;     for (int q = 0; q < 8; ++q) {
;       const int c = lane + 64 * q, row = c >> 4, c4 = (c & 15) * 4;
;       const long o = ((long)mt * 128 + wm * 64 + 32 * hp + row) * DM + nt * 128 + wn * 64 + c4;
;       const float4 rv = *(const float4*)(resid + o);
;       const f32x4 cv = *(const f32x4*)(sC + row * 68 + c4);
;       *(float4*)(out + o) = make_float4(rv.x + cv[0], rv.y + cv[1], rv.z + cv[2], rv.w + cv[3]);
;     }
;   }
	ds_write2_b32 v65, v60, v56 offset1:16
	ds_write2_b32 v65, v61, v57 offset0:68 offset1:84
	ds_write2_b32 v65, v62, v58 offset0:136 offset1:152
	ds_write2_b32 v65, v63, v59 offset0:204 offset1:220
	ds_write2_b32 v65, v52, v48 offset0:32 offset1:48
	ds_write2_b32 v65, v53, v49 offset0:100 offset1:116
	ds_write2_b32 v65, v54, v50 offset0:168 offset1:184
	ds_write2_b32 v65, v55, v51 offset0:236 offset1:252
	v_add_u32_e32 v48, 0x1000, v65
	v_add_u32_e32 v49, 0x1400, v65
	ds_write2_b32 v48, v44, v40 offset0:64 offset1:80
	ds_write2_b32 v48, v45, v41 offset0:132 offset1:148
	ds_write2_b32 v48, v46, v42 offset0:200 offset1:216
	ds_write2_b32 v49, v47, v43 offset0:12 offset1:28
	ds_write2_b32 v48, v36, v86 offset0:96 offset1:112
	ds_write2_b32 v48, v37, v87 offset0:164 offset1:180
	ds_write2_b32 v48, v38, v88 offset0:232 offset1:248
	ds_write2_b32 v49, v39, v89 offset0:44 offset1:60
	s_waitcnt lgkmcnt(0)
	s_barrier
	v_mad_u32_u24 v36, v67, s0, v64
	ds_read_b128 v[40:43], v36
	ds_read_b128 v[44:47], v36 offset:1088
	ds_read_b128 v[52:55], v36 offset:2176
	ds_read_b128 v[56:59], v36 offset:3264
	ds_read_b128 v[60:63], v36 offset:4352
	ds_read_b128 v[68:71], v36 offset:5440
	ds_read_b128 v[72:75], v36 offset:6528
	ds_read_b128 v[76:79], v36 offset:7616
	s_add_i32 s4, s4, s6
	s_cmp_lt_i32 s4, s5
	s_waitcnt vmcnt(8) lgkmcnt(0)
	v_pk_add_f32 v[40:41], v[106:107], v[40:41]
	v_pk_add_f32 v[42:43], v[108:109], v[42:43]
	global_store_dwordx4 v90, v[40:43], s[68:69] sc1
	v_pk_add_f32 v[44:45], v[110:111], v[44:45]
	v_pk_add_f32 v[46:47], v[112:113], v[46:47]
	global_store_dwordx4 v91, v[44:47], s[68:69] sc1
	v_pk_add_f32 v[52:53], v[114:115], v[52:53]
	v_pk_add_f32 v[54:55], v[116:117], v[54:55]
	global_store_dwordx4 v92, v[52:55], s[68:69] sc1
	v_pk_add_f32 v[56:57], v[118:119], v[56:57]
	v_pk_add_f32 v[58:59], v[120:121], v[58:59]
	global_store_dwordx4 v93, v[56:59], s[68:69] sc1
	v_pk_add_f32 v[60:61], v[122:123], v[60:61]
	v_pk_add_f32 v[62:63], v[124:125], v[62:63]
	global_store_dwordx4 v94, v[60:63], s[68:69] sc1
	v_pk_add_f32 v[68:69], v[126:127], v[68:69]
	v_pk_add_f32 v[70:71], v[128:129], v[70:71]
	global_store_dwordx4 v95, v[68:71], s[68:69] sc1
	v_pk_add_f32 v[72:73], v[130:131], v[72:73]
	v_pk_add_f32 v[74:75], v[132:133], v[74:75]
	global_store_dwordx4 v96, v[72:75], s[68:69] sc1
	v_pk_add_f32 v[76:77], v[134:135], v[76:77]
	v_pk_add_f32 v[78:79], v[136:137], v[78:79]
	global_store_dwordx4 v97, v[76:79], s[68:69] sc1
	s_barrier
	ds_write2_b32 v65, v24, v28 offset1:16
	ds_write2_b32 v65, v25, v29 offset0:68 offset1:84
	ds_write2_b32 v65, v26, v30 offset0:136 offset1:152
	ds_write2_b32 v65, v27, v31 offset0:204 offset1:220
	ds_write2_b32 v65, v16, v20 offset0:32 offset1:48
	ds_write2_b32 v65, v17, v21 offset0:100 offset1:116
	ds_write2_b32 v65, v18, v22 offset0:168 offset1:184
	ds_write2_b32 v65, v19, v23 offset0:236 offset1:252
	ds_write2_b32 v48, v8, v12 offset0:64 offset1:80
	ds_write2_b32 v48, v9, v13 offset0:132 offset1:148
	ds_write2_b32 v48, v10, v14 offset0:200 offset1:216
	ds_write2_b32 v49, v11, v15 offset0:12 offset1:28
	ds_write2_b32 v48, v0, v4 offset0:96 offset1:112
	ds_write2_b32 v48, v1, v5 offset0:164 offset1:180
	ds_write2_b32 v48, v2, v6 offset0:232 offset1:248
	ds_write2_b32 v49, v3, v7 offset0:44 offset1:60
	s_waitcnt lgkmcnt(0)
	s_barrier
	ds_read_b128 v[0:3], v36
	ds_read_b128 v[4:7], v36 offset:1088
	ds_read_b128 v[8:11], v36 offset:2176
	ds_read_b128 v[12:15], v36 offset:3264
	ds_read_b128 v[16:19], v36 offset:4352
	ds_read_b128 v[20:23], v36 offset:5440
	ds_read_b128 v[24:27], v36 offset:6528
	ds_read_b128 v[28:31], v36 offset:7616
	s_waitcnt vmcnt(8) lgkmcnt(0)
	v_pk_add_f32 v[0:1], v[210:211], v[0:1]
	v_pk_add_f32 v[2:3], v[212:213], v[2:3]
	global_store_dwordx4 v98, v[0:3], s[68:69] sc1
	v_pk_add_f32 v[4:5], v[214:215], v[4:5]
	v_pk_add_f32 v[6:7], v[216:217], v[6:7]
	global_store_dwordx4 v99, v[4:7], s[68:69] sc1
	v_pk_add_f32 v[8:9], v[218:219], v[8:9]
	v_pk_add_f32 v[10:11], v[220:221], v[10:11]
	global_store_dwordx4 v100, v[8:11], s[68:69] sc1
	v_pk_add_f32 v[12:13], v[222:223], v[12:13]
	v_pk_add_f32 v[14:15], v[224:225], v[14:15]
	global_store_dwordx4 v101, v[12:15], s[68:69] sc1
	v_pk_add_f32 v[16:17], v[226:227], v[16:17]
	v_pk_add_f32 v[18:19], v[228:229], v[18:19]
	global_store_dwordx4 v102, v[16:19], s[68:69] sc1
	v_pk_add_f32 v[20:21], v[230:231], v[20:21]
	v_pk_add_f32 v[22:23], v[232:233], v[22:23]
	global_store_dwordx4 v103, v[20:23], s[68:69] sc1
	v_pk_add_f32 v[24:25], v[234:235], v[24:25]
	v_pk_add_f32 v[26:27], v[236:237], v[26:27]
	global_store_dwordx4 v104, v[24:27], s[68:69] sc1
	v_pk_add_f32 v[28:29], v[238:239], v[28:29]
	v_pk_add_f32 v[30:31], v[240:241], v[30:31]
	global_store_dwordx4 v105, v[28:31], s[68:69] sc1
	s_cbranch_scc1 .LBB0_36

;     ...
; #pragma unroll 1
;     for (int kt = 0; kt < nk - 1; ++kt) {
;       asm volatile("s_waitcnt vmcnt(0) lgkmcnt(0)" ::: "memory");
;       __builtin_amdgcn_s_barrier();
;       asm volatile("" ::: "memory");
;       G3_STEP(kt, true)
;     }
.LBB0_65:
	s_lshl_b32 s12, s3, 1
	s_and_b32 s12, s12, 0x8000
	v_lshl_or_b32 v87, v86, 1, s12
	s_waitcnt vmcnt(0) lgkmcnt(0)
	s_barrier
	v_add3_u32 v100, v87, v84, v83
	v_add3_u32 v87, v87, v82, v83
	ds_read_b128 v[88:91], v100
	ds_read_b128 v[92:95], v100 offset:2048
	ds_read_b128 v[96:99], v100 offset:4096
	ds_read_b128 v[100:103], v100 offset:6144
	ds_read_b128 v[104:107], v87 offset:16384
	ds_read_b128 v[108:111], v87 offset:18432
	ds_read_b128 v[112:115], v87 offset:20480
	ds_read_b128 v[116:119], v87 offset:22528
	v_lshl_or_b32 v87, v85, 1, s12
	v_add3_u32 v132, v87, v84, v83
	v_add3_u32 v87, v87, v82, v83
	ds_read_b128 v[120:123], v132
	ds_read_b128 v[124:127], v132 offset:2048
	ds_read_b128 v[128:131], v132 offset:4096
	ds_read_b128 v[132:135], v132 offset:6144
	ds_read_b128 v[136:139], v87 offset:16384
	ds_read_b128 v[140:143], v87 offset:18432
	ds_read_b128 v[144:147], v87 offset:20480
	ds_read_b128 v[148:151], v87 offset:22528
	s_setprio 1
	s_andn2_b32 s12, 0x8000, s11
	s_waitcnt lgkmcnt(11)
	v_mfma_f32_16x16x32_bf16 v[60:63], v[88:91], v[104:107], v[60:63]
	s_add_i32 s12, s1, s12
	v_lshl_add_u64 v[172:173], v[64:65], 0, s[6:7]
	s_mov_b32 m0, s12
	s_nop 0
	global_load_lds_dwordx4 v[172:173], off
	s_waitcnt lgkmcnt(10)
	v_mfma_f32_16x16x32_bf16 v[56:59], v[88:91], v[108:111], v[56:59]
	v_lshl_add_u64 v[152:153], v[78:79], 0, s[6:7]
	v_lshl_add_u64 v[154:155], v[76:77], 0, s[6:7]
	v_lshl_add_u64 v[156:157], v[74:75], 0, s[6:7]
	v_lshl_add_u64 v[158:159], v[72:73], 0, s[6:7]
	v_lshl_add_u64 v[166:167], v[70:71], 0, s[6:7]
	v_lshl_add_u64 v[168:169], v[68:69], 0, s[6:7]
	v_lshl_add_u64 v[170:171], v[66:67], 0, s[6:7]
	s_waitcnt lgkmcnt(9)
	v_mfma_f32_16x16x32_bf16 v[52:55], v[88:91], v[112:115], v[52:55]
	s_add_i32 s13, s12, 0x400
	s_mov_b32 m0, s13
	s_nop 0
	global_load_lds_dwordx4 v[168:169], off
	s_waitcnt lgkmcnt(8)
	v_mfma_f32_16x16x32_bf16 v[48:51], v[88:91], v[116:119], v[48:51]
	v_mfma_f32_16x16x32_bf16 v[44:47], v[92:95], v[104:107], v[44:47]
	s_add_i32 s13, s12, 0x800
	s_mov_b32 m0, s13
	s_nop 0
	global_load_lds_dwordx4 v[156:157], off
	v_mfma_f32_16x16x32_bf16 v[40:43], v[92:95], v[108:111], v[40:43]
	v_mfma_f32_16x16x32_bf16 v[36:39], v[92:95], v[112:115], v[36:39]
	s_add_i32 s13, s12, 0xc00
	s_mov_b32 m0, s13
	s_nop 0
	global_load_lds_dwordx4 v[166:167], off
	v_mfma_f32_16x16x32_bf16 v[32:35], v[92:95], v[116:119], v[32:35]
	v_mfma_f32_16x16x32_bf16 v[28:31], v[96:99], v[104:107], v[28:31]
	s_add_i32 s13, s12, 0x4000
	s_mov_b32 m0, s13
	s_nop 0
	global_load_lds_dwordx4 v[154:155], off
	v_mfma_f32_16x16x32_bf16 v[24:27], v[96:99], v[108:111], v[24:27]
	v_mfma_f32_16x16x32_bf16 v[20:23], v[96:99], v[112:115], v[20:23]
	s_add_i32 s13, s12, 0x4400
	s_mov_b32 m0, s13
	s_nop 0
	global_load_lds_dwordx4 v[158:159], off
	v_mfma_f32_16x16x32_bf16 v[16:19], v[96:99], v[116:119], v[16:19]
	v_mfma_f32_16x16x32_bf16 v[12:15], v[100:103], v[104:107], v[12:15]
	s_add_i32 s13, s12, 0x4800
	s_mov_b32 m0, s13
	s_nop 0
	global_load_lds_dwordx4 v[152:153], off
	v_mfma_f32_16x16x32_bf16 v[8:11], v[100:103], v[108:111], v[8:11]
	v_mfma_f32_16x16x32_bf16 v[4:7], v[100:103], v[112:115], v[4:7]
	s_addk_i32 s12, 0x4c00
	s_mov_b32 m0, s12
	s_nop 0
	global_load_lds_dwordx4 v[170:171], off
	v_mfma_f32_16x16x32_bf16 v[0:3], v[100:103], v[116:119], v[0:3]
	s_waitcnt lgkmcnt(3)
	v_mfma_f32_16x16x32_bf16 v[60:63], v[120:123], v[136:139], v[60:63]
	s_waitcnt lgkmcnt(2)
	v_mfma_f32_16x16x32_bf16 v[56:59], v[120:123], v[140:143], v[56:59]
	s_waitcnt lgkmcnt(1)
	v_mfma_f32_16x16x32_bf16 v[52:55], v[120:123], v[144:147], v[52:55]
	s_waitcnt lgkmcnt(0)
	v_mfma_f32_16x16x32_bf16 v[48:51], v[120:123], v[148:151], v[48:51]
	v_mfma_f32_16x16x32_bf16 v[44:47], v[124:127], v[136:139], v[44:47]
	v_mfma_f32_16x16x32_bf16 v[40:43], v[124:127], v[140:143], v[40:43]
	v_mfma_f32_16x16x32_bf16 v[36:39], v[124:127], v[144:147], v[36:39]
	v_mfma_f32_16x16x32_bf16 v[32:35], v[124:127], v[148:151], v[32:35]
	v_mfma_f32_16x16x32_bf16 v[28:31], v[128:131], v[136:139], v[28:31]
	v_mfma_f32_16x16x32_bf16 v[24:27], v[128:131], v[140:143], v[24:27]
	v_mfma_f32_16x16x32_bf16 v[20:23], v[128:131], v[144:147], v[20:23]
	v_mfma_f32_16x16x32_bf16 v[16:19], v[128:131], v[148:151], v[16:19]
	v_mfma_f32_16x16x32_bf16 v[12:15], v[132:135], v[136:139], v[12:15]
	v_mfma_f32_16x16x32_bf16 v[8:11], v[132:135], v[140:143], v[8:11]
	v_mfma_f32_16x16x32_bf16 v[4:7], v[132:135], v[144:147], v[4:7]
	v_mfma_f32_16x16x32_bf16 v[0:3], v[132:135], v[148:151], v[0:3]
	s_setprio 0
	s_add_i32 s11, s11, 0x8000
	s_add_u32 s6, s6, 0x80
	s_addc_u32 s7, s7, 0
	s_addk_i32 s3, 0x4000
	s_cmpk_lg_i32 s6, 0x780
	s_cbranch_scc1 .LBB0_65
	v_lshlrev_b32_e32 v86, 1, v86
	v_lshlrev_b32_e32 v85, 1, v85
	s_waitcnt vmcnt(0) lgkmcnt(0)
	s_barrier
; DI float siluf_(float x) { return x * sigmoidf_(x); }
; DI void ffn1_tile(const Params& P, int l, int it, u16* sA, u16* sB) {
;     ...
;   __syncthreads();
; #pragma unroll
;   for (int mi = 0; mi < 4; ++mi)
; #pragma unroll
;     for (int ni = 0; ni < 2; ++ni)
; #pragma unroll
;       for (int j = 0; j < 4; ++j)
;         sA[(wm * 64 + 16 * mi + 4 * quad + j) * 72 + wn * 32 + 16 * ni + r16] = f2bf(siluf_(acc[mi][ni][j]) * acc[mi][ni + 2][j]);
	v_add3_u32 v76, v86, v84, v83
	v_add3_u32 v98, v86, v82, v83
	v_add3_u32 v84, v85, v84, v83
	v_add3_u32 v126, v85, v82, v83
	ds_read_b128 v[64:67], v76 offset:32768
	ds_read_b128 v[68:71], v76 offset:34816
	ds_read_b128 v[72:75], v76 offset:36864
	ds_read_b128 v[76:79], v76 offset:38912
	ds_read_b128 v[86:89], v98 offset:49152
	ds_read_b128 v[90:93], v98 offset:51200
	ds_read_b128 v[94:97], v98 offset:53248
	ds_read_b128 v[98:101], v98 offset:55296
	ds_read_b128 v[102:105], v84 offset:32768
	ds_read_b128 v[106:109], v84 offset:34816
	ds_read_b128 v[110:113], v84 offset:36864
	ds_read_b128 v[114:117], v84 offset:38912
	ds_read_b128 v[82:85], v126 offset:49152
	ds_read_b128 v[118:121], v126 offset:51200
	ds_read_b128 v[122:125], v126 offset:53248
	ds_read_b128 v[126:129], v126 offset:55296
	v_and_b32_e32 v138, 15, v80
	s_setprio 1
	s_waitcnt lgkmcnt(11)
	v_mfma_f32_16x16x32_bf16 v[60:63], v[64:67], v[86:89], v[60:63]
	s_waitcnt lgkmcnt(10)
	v_mfma_f32_16x16x32_bf16 v[56:59], v[64:67], v[90:93], v[56:59]
	s_waitcnt lgkmcnt(9)
	v_mfma_f32_16x16x32_bf16 v[52:55], v[64:67], v[94:97], v[52:55]
	s_waitcnt lgkmcnt(8)
	v_mfma_f32_16x16x32_bf16 v[64:67], v[64:67], v[98:101], v[48:51]
	v_mfma_f32_16x16x32_bf16 v[44:47], v[68:71], v[86:89], v[44:47]
	v_mfma_f32_16x16x32_bf16 v[130:133], v[68:71], v[90:93], v[40:43]
	v_mfma_f32_16x16x32_bf16 v[36:39], v[68:71], v[94:97], v[36:39]
	v_mfma_f32_16x16x32_bf16 v[68:71], v[68:71], v[98:101], v[32:35]
	v_mfma_f32_16x16x32_bf16 v[28:31], v[72:75], v[86:89], v[28:31]
	v_mfma_f32_16x16x32_bf16 v[134:137], v[72:75], v[90:93], v[24:27]
	v_mfma_f32_16x16x32_bf16 v[20:23], v[72:75], v[94:97], v[20:23]
	v_mfma_f32_16x16x32_bf16 v[72:75], v[72:75], v[98:101], v[16:19]
	v_mfma_f32_16x16x32_bf16 v[12:15], v[76:79], v[86:89], v[12:15]
	v_mfma_f32_16x16x32_bf16 v[86:89], v[76:79], v[90:93], v[8:11]
	v_mfma_f32_16x16x32_bf16 v[4:7], v[76:79], v[94:97], v[4:7]
	v_mfma_f32_16x16x32_bf16 v[76:79], v[76:79], v[98:101], v[0:3]
	s_waitcnt lgkmcnt(2)
	v_mfma_f32_16x16x32_bf16 v[0:3], v[114:117], v[118:121], v[86:89]
	v_mfma_f32_16x16x32_bf16 v[60:63], v[102:105], v[82:85], v[60:63]
	v_mfma_f32_16x16x32_bf16 v[48:51], v[102:105], v[118:121], v[56:59]
	s_waitcnt lgkmcnt(1)
	v_mfma_f32_16x16x32_bf16 v[90:93], v[102:105], v[122:125], v[52:55]
	s_waitcnt lgkmcnt(0)
	v_mfma_f32_16x16x32_bf16 v[52:55], v[102:105], v[126:129], v[64:67]
	v_mfma_f32_16x16x32_bf16 v[40:43], v[106:109], v[82:85], v[44:47]
	v_mfma_f32_16x16x32_bf16 v[32:35], v[106:109], v[118:121], v[130:133]
	v_mfma_f32_16x16x32_bf16 v[44:47], v[106:109], v[122:125], v[36:39]
	v_mfma_f32_16x16x32_bf16 v[36:39], v[106:109], v[126:129], v[68:71]
	v_mfma_f32_16x16x32_bf16 v[24:27], v[110:113], v[82:85], v[28:31]
	v_mfma_f32_16x16x32_bf16 v[16:19], v[110:113], v[118:121], v[134:137]
	v_mfma_f32_16x16x32_bf16 v[28:31], v[110:113], v[122:125], v[20:23]
	v_mfma_f32_16x16x32_bf16 v[20:23], v[110:113], v[126:129], v[72:75]
	v_mfma_f32_16x16x32_bf16 v[8:11], v[114:117], v[82:85], v[12:15]
	v_mfma_f32_16x16x32_bf16 v[12:15], v[114:117], v[122:125], v[4:7]
	v_mfma_f32_16x16x32_bf16 v[4:7], v[114:117], v[126:129], v[76:79]
	s_setprio 0
	v_lshrrev_b32_e32 v56, 2, v80
	v_and_b32_e32 v56, 12, v56
	s_mov_b32 s1, 0xfffffc0
	v_and_or_b32 v57, v81, s1, v56
	v_lshlrev_b32_e32 v56, 1, v138
	v_and_or_b32 v56, v80, 64, v56
	v_mad_u64_u32 v[56:57], s[6:7], v57, s54, v[56:57]
	v_mul_f32_e32 v57, 0xbfb8aa3b, v61
	v_exp_f32_e32 v57, v57
	s_barrier
	v_add_f32_e32 v57, 1.0, v57
	v_rcp_f32_e32 v57, v57
	v_mul_f32_e32 v58, 0xbfb8aa3b, v60
	v_exp_f32_e32 v58, v58
	s_add_u32 s1, s70, s4
	v_mul_f32_e32 v57, v61, v57
	v_mul_f32_e32 v57, v91, v57
	v_cvt_pk_bf16_f32 v57, v57, s0
	ds_write_b16 v56, v57 offset:144
	v_mul_f32_e32 v57, 0xbfb8aa3b, v62
	v_exp_f32_e32 v57, v57
	v_add_f32_e32 v58, 1.0, v58
	v_rcp_f32_e32 v58, v58
	s_addc_u32 s3, s71, s5
	v_add_f32_e32 v57, 1.0, v57
	v_rcp_f32_e32 v57, v57
	v_mul_f32_e32 v58, v60, v58
	s_mul_hi_i32 s4, s2, 0xb0000
	s_mul_i32 s2, s2, 0xb0000
	v_mul_f32_e32 v57, v62, v57
	v_mul_f32_e32 v57, v92, v57
	v_cvt_pk_bf16_f32 v57, v57, s0
	ds_write_b16 v56, v57 offset:288
	v_mul_f32_e32 v57, 0xbfb8aa3b, v63
	v_exp_f32_e32 v57, v57
	v_mul_f32_e32 v58, v90, v58
	s_add_u32 s2, s1, s2
	v_cvt_pk_bf16_f32 v58, v58, s0
	v_add_f32_e32 v57, 1.0, v57
	v_rcp_f32_e32 v57, v57
	s_addc_u32 s3, s3, s4
	ds_write_b16 v56, v58
	v_mul_f32_e32 v57, v63, v57
	v_mul_f32_e32 v57, v93, v57
	v_cvt_pk_bf16_f32 v57, v57, s0
	ds_write_b16 v56, v57 offset:432
	v_mul_f32_e32 v57, 0xbfb8aa3b, v48
	v_exp_f32_e32 v57, v57
	s_nop 0
	v_add_f32_e32 v57, 1.0, v57
	v_rcp_f32_e32 v57, v57
	s_nop 0
	v_mul_f32_e32 v48, v48, v57
	v_mul_f32_e32 v48, v52, v48
	v_cvt_pk_bf16_f32 v48, v48, s0
	ds_write_b16 v56, v48 offset:32
	v_mul_f32_e32 v48, 0xbfb8aa3b, v49
	v_exp_f32_e32 v48, v48
	s_nop 0
	v_add_f32_e32 v48, 1.0, v48
	v_rcp_f32_e32 v48, v48
	s_nop 0
	v_mul_f32_e32 v48, v49, v48
	v_mul_f32_e32 v48, v53, v48
	v_cvt_pk_bf16_f32 v48, v48, s0
	ds_write_b16 v56, v48 offset:176
	v_mul_f32_e32 v48, 0xbfb8aa3b, v50
	v_exp_f32_e32 v48, v48
	s_nop 0
	v_add_f32_e32 v48, 1.0, v48
	v_rcp_f32_e32 v48, v48
	s_nop 0
	v_mul_f32_e32 v48, v50, v48
	v_mul_f32_e32 v48, v54, v48
	v_cvt_pk_bf16_f32 v48, v48, s0
	ds_write_b16 v56, v48 offset:320
	v_mul_f32_e32 v48, 0xbfb8aa3b, v51
	v_exp_f32_e32 v48, v48
	s_nop 0
	v_add_f32_e32 v48, 1.0, v48
	v_rcp_f32_e32 v48, v48
	s_nop 0
	v_mul_f32_e32 v48, v51, v48
	v_mul_f32_e32 v48, v55, v48
	v_cvt_pk_bf16_f32 v48, v48, s0
	ds_write_b16 v56, v48 offset:464
	v_mul_f32_e32 v48, 0xbfb8aa3b, v40
	v_exp_f32_e32 v48, v48
	s_nop 0
	v_add_f32_e32 v48, 1.0, v48
	v_rcp_f32_e32 v48, v48
	s_nop 0
	v_mul_f32_e32 v40, v40, v48
; DI float siluf_(float x) { return x * sigmoidf_(x); }
; template <int NCOLS>
; DI void store_tile_bf16(const u16* sC, u16* gdst, long ld, int rows_valid) {
;     ...
; #pragma unroll
;   for (int q = 0; q < (128 * CPR) / 256; ++q) {
;     const int c = tid + 256 * q, row = c / CPR, ch = c % CPR;
;     if (row < rows_valid) *(uint4*)(gdst + (long)row * ld + ch * 8) = *(const uint4*)(sC + row * LS + ch * 8);
;   }
; DI void ffn1_tile(const Params& P, int l, int it, u16* sA, u16* sB) {
;     ...
; #pragma unroll
;   for (int mi = 0; mi < 4; ++mi)
; #pragma unroll
;     for (int ni = 0; ni < 2; ++ni)
; #pragma unroll
;       for (int j = 0; j < 4; ++j)
;         sA[(wm * 64 + 16 * mi + 4 * quad + j) * 72 + wn * 32 + 16 * ni + r16] = f2bf(siluf_(acc[mi][ni][j]) * acc[mi][ni + 2][j]);
;   __syncthreads();
;   store_tile_bf16<64>(sA, ACT + (long)mt * 128 * DFF + nt * 64, DFF, 128);
	v_mul_f32_e32 v40, v44, v40
	v_cvt_pk_bf16_f32 v40, v40, s0
	ds_write_b16 v56, v40 offset:2304
	v_mul_f32_e32 v40, 0xbfb8aa3b, v41
	v_exp_f32_e32 v40, v40
	s_nop 0
	v_add_f32_e32 v40, 1.0, v40
	v_rcp_f32_e32 v40, v40
	s_nop 0
	v_mul_f32_e32 v40, v41, v40
	v_mul_f32_e32 v40, v45, v40
	v_cvt_pk_bf16_f32 v40, v40, s0
	ds_write_b16 v56, v40 offset:2448
	v_mul_f32_e32 v40, 0xbfb8aa3b, v42
	v_exp_f32_e32 v40, v40
	s_nop 0
	v_add_f32_e32 v40, 1.0, v40
	v_rcp_f32_e32 v40, v40
	s_nop 0
	v_mul_f32_e32 v40, v42, v40
	v_mul_f32_e32 v40, v46, v40
	v_cvt_pk_bf16_f32 v40, v40, s0
	ds_write_b16 v56, v40 offset:2592
	v_mul_f32_e32 v40, 0xbfb8aa3b, v43
	v_exp_f32_e32 v40, v40
	s_nop 0
	v_add_f32_e32 v40, 1.0, v40
	v_rcp_f32_e32 v40, v40
	s_nop 0
	v_mul_f32_e32 v40, v43, v40
	v_mul_f32_e32 v40, v47, v40
	v_cvt_pk_bf16_f32 v40, v40, s0
	ds_write_b16 v56, v40 offset:2736
	v_mul_f32_e32 v40, 0xbfb8aa3b, v32
	v_exp_f32_e32 v40, v40
	s_nop 0
	v_add_f32_e32 v40, 1.0, v40
	v_rcp_f32_e32 v40, v40
	s_nop 0
	v_mul_f32_e32 v32, v32, v40
	v_mul_f32_e32 v32, v36, v32
	v_cvt_pk_bf16_f32 v32, v32, s0
	ds_write_b16 v56, v32 offset:2336
	v_mul_f32_e32 v32, 0xbfb8aa3b, v33
	v_exp_f32_e32 v32, v32
	s_nop 0
	v_add_f32_e32 v32, 1.0, v32
	v_rcp_f32_e32 v32, v32
	s_nop 0
	v_mul_f32_e32 v32, v33, v32
	v_mul_f32_e32 v32, v37, v32
	v_cvt_pk_bf16_f32 v32, v32, s0
	ds_write_b16 v56, v32 offset:2480
	v_mul_f32_e32 v32, 0xbfb8aa3b, v34
	v_exp_f32_e32 v32, v32
	s_nop 0
	v_add_f32_e32 v32, 1.0, v32
	v_rcp_f32_e32 v32, v32
	s_nop 0
	v_mul_f32_e32 v32, v34, v32
	v_mul_f32_e32 v32, v38, v32
	v_cvt_pk_bf16_f32 v32, v32, s0
	ds_write_b16 v56, v32 offset:2624
	v_mul_f32_e32 v32, 0xbfb8aa3b, v35
	v_exp_f32_e32 v32, v32
	s_nop 0
	v_add_f32_e32 v32, 1.0, v32
	v_rcp_f32_e32 v32, v32
	s_nop 0
	v_mul_f32_e32 v32, v35, v32
	v_mul_f32_e32 v32, v39, v32
	v_cvt_pk_bf16_f32 v32, v32, s0
	ds_write_b16 v56, v32 offset:2768
	v_mul_f32_e32 v32, 0xbfb8aa3b, v24
	v_exp_f32_e32 v32, v32
	s_nop 0
	v_add_f32_e32 v32, 1.0, v32
	v_rcp_f32_e32 v32, v32
	s_nop 0
	v_mul_f32_e32 v24, v24, v32
	v_mul_f32_e32 v24, v28, v24
	v_cvt_pk_bf16_f32 v24, v24, s0
	ds_write_b16 v56, v24 offset:4608
	v_mul_f32_e32 v24, 0xbfb8aa3b, v25
	v_exp_f32_e32 v24, v24
	s_nop 0
	v_add_f32_e32 v24, 1.0, v24
	v_rcp_f32_e32 v24, v24
	s_nop 0
	v_mul_f32_e32 v24, v25, v24
	v_mul_f32_e32 v24, v29, v24
	v_cvt_pk_bf16_f32 v24, v24, s0
	ds_write_b16 v56, v24 offset:4752
	v_mul_f32_e32 v24, 0xbfb8aa3b, v26
	v_exp_f32_e32 v24, v24
	s_nop 0
	v_add_f32_e32 v24, 1.0, v24
	v_rcp_f32_e32 v24, v24
	s_nop 0
	v_mul_f32_e32 v24, v26, v24
	v_mul_f32_e32 v24, v30, v24
	v_cvt_pk_bf16_f32 v24, v24, s0
	ds_write_b16 v56, v24 offset:4896
	v_mul_f32_e32 v24, 0xbfb8aa3b, v27
	v_exp_f32_e32 v24, v24
	s_nop 0
	v_add_f32_e32 v24, 1.0, v24
	v_rcp_f32_e32 v24, v24
	s_nop 0
	v_mul_f32_e32 v24, v27, v24
	v_mul_f32_e32 v24, v31, v24
	v_cvt_pk_bf16_f32 v24, v24, s0
	ds_write_b16 v56, v24 offset:5040
	v_mul_f32_e32 v24, 0xbfb8aa3b, v16
	v_exp_f32_e32 v24, v24
	s_nop 0
	v_add_f32_e32 v24, 1.0, v24
	v_rcp_f32_e32 v24, v24
	s_nop 0
	v_mul_f32_e32 v16, v16, v24
	v_mul_f32_e32 v16, v20, v16
	v_cvt_pk_bf16_f32 v16, v16, s0
	ds_write_b16 v56, v16 offset:4640
	v_mul_f32_e32 v16, 0xbfb8aa3b, v17
	v_exp_f32_e32 v16, v16
	s_nop 0
	v_add_f32_e32 v16, 1.0, v16
	v_rcp_f32_e32 v16, v16
	s_nop 0
	v_mul_f32_e32 v16, v17, v16
	v_mul_f32_e32 v16, v21, v16
	v_cvt_pk_bf16_f32 v16, v16, s0
	ds_write_b16 v56, v16 offset:4784
	v_mul_f32_e32 v16, 0xbfb8aa3b, v18
	v_exp_f32_e32 v16, v16
	s_nop 0
	v_add_f32_e32 v16, 1.0, v16
	v_rcp_f32_e32 v16, v16
	s_nop 0
	v_mul_f32_e32 v16, v18, v16
	v_mul_f32_e32 v16, v22, v16
	v_cvt_pk_bf16_f32 v16, v16, s0
	ds_write_b16 v56, v16 offset:4928
	v_mul_f32_e32 v16, 0xbfb8aa3b, v19
	v_exp_f32_e32 v16, v16
	s_nop 0
	v_add_f32_e32 v16, 1.0, v16
	v_rcp_f32_e32 v16, v16
	s_nop 0
	v_mul_f32_e32 v16, v19, v16
	v_mul_f32_e32 v16, v23, v16
	v_cvt_pk_bf16_f32 v16, v16, s0
	ds_write_b16 v56, v16 offset:5072
	v_mul_f32_e32 v16, 0xbfb8aa3b, v8
	v_exp_f32_e32 v16, v16
	s_nop 0
	v_add_f32_e32 v16, 1.0, v16
	v_rcp_f32_e32 v16, v16
	s_nop 0
	v_mul_f32_e32 v8, v8, v16
	v_mul_f32_e32 v8, v12, v8
	v_cvt_pk_bf16_f32 v8, v8, s0
	ds_write_b16 v56, v8 offset:6912
	v_mul_f32_e32 v8, 0xbfb8aa3b, v9
	v_exp_f32_e32 v8, v8
	s_nop 0
	v_add_f32_e32 v8, 1.0, v8
	v_rcp_f32_e32 v8, v8
	s_nop 0
	v_mul_f32_e32 v8, v9, v8
	v_mul_f32_e32 v8, v13, v8
	v_cvt_pk_bf16_f32 v8, v8, s0
	ds_write_b16 v56, v8 offset:7056
	v_mul_f32_e32 v8, 0xbfb8aa3b, v10
	v_exp_f32_e32 v8, v8
	s_nop 0
	v_add_f32_e32 v8, 1.0, v8
	v_rcp_f32_e32 v8, v8
	s_nop 0
	v_mul_f32_e32 v8, v10, v8
	v_mul_f32_e32 v8, v14, v8
	v_cvt_pk_bf16_f32 v8, v8, s0
	ds_write_b16 v56, v8 offset:7200
	v_mul_f32_e32 v8, 0xbfb8aa3b, v11
	v_exp_f32_e32 v8, v8
	s_nop 0
	v_add_f32_e32 v8, 1.0, v8
	v_rcp_f32_e32 v8, v8
	s_nop 0
	v_mul_f32_e32 v8, v11, v8
	v_mul_f32_e32 v8, v15, v8
	v_cvt_pk_bf16_f32 v8, v8, s0
	ds_write_b16 v56, v8 offset:7344
	v_mul_f32_e32 v8, 0xbfb8aa3b, v0
	v_exp_f32_e32 v8, v8
	s_nop 0
	v_add_f32_e32 v8, 1.0, v8
	v_rcp_f32_e32 v8, v8
	s_nop 0
	v_mul_f32_e32 v0, v0, v8
	v_mul_f32_e32 v0, v4, v0
	v_cvt_pk_bf16_f32 v0, v0, s0
	ds_write_b16 v56, v0 offset:6944
	v_mul_f32_e32 v0, 0xbfb8aa3b, v1
	v_exp_f32_e32 v0, v0
	s_nop 0
	v_add_f32_e32 v0, 1.0, v0
	v_rcp_f32_e32 v0, v0
	s_nop 0
	v_mul_f32_e32 v0, v1, v0
	v_mul_f32_e32 v0, v5, v0
	v_cvt_pk_bf16_f32 v0, v0, s0
	ds_write_b16 v56, v0 offset:7088
	v_mul_f32_e32 v0, 0xbfb8aa3b, v2
	v_exp_f32_e32 v0, v0
	s_nop 0
	v_add_f32_e32 v0, 1.0, v0
	v_rcp_f32_e32 v0, v0
	s_nop 0
	v_mul_f32_e32 v0, v2, v0
	v_mul_f32_e32 v0, v6, v0
	v_cvt_pk_bf16_f32 v0, v0, s0
	ds_write_b16 v56, v0 offset:7232
	v_mul_f32_e32 v0, 0xbfb8aa3b, v3
	v_exp_f32_e32 v0, v0
	s_nop 0
	v_add_f32_e32 v0, 1.0, v0
	v_rcp_f32_e32 v0, v0
	s_nop 0
	v_mul_f32_e32 v0, v3, v0
	v_mul_f32_e32 v0, v7, v0
	v_cvt_pk_bf16_f32 v0, v0, s0
	s_lshl_b32 s0, s0, 6
	s_ashr_i32 s1, s0, 31
	s_lshl_b64 s[0:1], s[0:1], 1
	s_add_u32 s0, s2, s0
	s_addc_u32 s1, s3, s1
	ds_write_b16 v56, v0 offset:7376
	s_add_u32 s0, s0, 0x4000000
	v_mov_b32_e32 v0, v160
	s_movk_i32 s2, 0x400
	s_waitcnt lgkmcnt(0)
	s_barrier
	s_addc_u32 s1, s1, 0
	s_nop 0
	v_cmp_gt_i32_e32 vcc, s2, v0
	s_and_saveexec_b64 s[2:3], vcc
	s_cbranch_execz .LBB0_68
	v_ashrrev_i32_e32 v1, 31, v0
	v_lshrrev_b32_e32 v1, 29, v1
	v_add_u32_e32 v1, v0, v1
	v_ashrrev_i32_e32 v6, 3, v1
	v_and_b32_e32 v1, -8, v1
	v_sub_u32_e32 v1, v0, v1
	v_mul_lo_u32 v4, v6, s54
	v_lshlrev_b32_e32 v2, 3, v1
	v_lshl_add_u32 v1, v1, 4, v4
	v_mov_b64_e32 v[4:5], s[0:1]
	s_movk_i32 s4, 0x1600
	v_ashrrev_i32_e32 v3, 31, v2
	v_mad_i64_i32 v[4:5], s[4:5], v6, s4, v[4:5]
	v_lshl_add_u64 v[6:7], v[2:3], 1, v[4:5]
	ds_read_b128 v[2:5], v1
	s_waitcnt lgkmcnt(0)
	global_store_dwordx4 v[6:7], v[2:5], off sc1
; template <int NCOLS>
; DI void store_tile_bf16(const u16* sC, u16* gdst, long ld, int rows_valid) {
;     ...
; #pragma unroll
;   for (int q = 0; q < (128 * CPR) / 256; ++q) {
;     const int c = tid + 256 * q, row = c / CPR, ch = c % CPR;
;     if (row < rows_valid) *(uint4*)(gdst + (long)row * ld + ch * 8) = *(const uint4*)(sC + row * LS + ch * 8);
;   }
.LBB0_68:
	s_or_b64 exec, exec, s[2:3]
	s_movk_i32 s2, 0x300
	v_cmp_gt_i32_e32 vcc, s2, v0
	s_and_saveexec_b64 s[2:3], vcc
	s_cbranch_execz .LBB0_70
	v_add_u32_e32 v1, 0x100, v0
	v_ashrrev_i32_e32 v2, 31, v1
	v_lshrrev_b32_e32 v2, 29, v2
	v_add_u32_e32 v2, v1, v2
	v_ashrrev_i32_e32 v6, 3, v2
	v_and_b32_e32 v2, -8, v2
	v_sub_u32_e32 v1, v1, v2
	v_mul_lo_u32 v4, v6, s54
	v_lshlrev_b32_e32 v2, 3, v1
	v_lshl_add_u32 v1, v1, 4, v4
	v_mov_b64_e32 v[4:5], s[0:1]
	s_movk_i32 s4, 0x1600
	v_ashrrev_i32_e32 v3, 31, v2
	v_mad_i64_i32 v[4:5], s[4:5], v6, s4, v[4:5]
	v_lshl_add_u64 v[6:7], v[2:3], 1, v[4:5]
	ds_read_b128 v[2:5], v1
	s_waitcnt lgkmcnt(0)
	global_store_dwordx4 v[6:7], v[2:5], off sc1
.LBB0_70:
	s_or_b64 exec, exec, s[2:3]
	s_movk_i32 s2, 0x200
	v_cmp_gt_i32_e32 vcc, s2, v0
	s_and_saveexec_b64 s[2:3], vcc
	s_cbranch_execz .LBB0_72
	v_add_u32_e32 v1, 0x200, v0
	v_ashrrev_i32_e32 v2, 31, v1
	v_lshrrev_b32_e32 v2, 29, v2
	v_add_u32_e32 v2, v1, v2
	v_ashrrev_i32_e32 v6, 3, v2
	v_and_b32_e32 v2, -8, v2
	v_sub_u32_e32 v1, v1, v2
	v_mul_lo_u32 v4, v6, s54
	v_lshlrev_b32_e32 v2, 3, v1
	v_lshl_add_u32 v1, v1, 4, v4
	v_mov_b64_e32 v[4:5], s[0:1]
	s_movk_i32 s4, 0x1600
	v_ashrrev_i32_e32 v3, 31, v2
	v_mad_i64_i32 v[4:5], s[4:5], v6, s4, v[4:5]
	v_lshl_add_u64 v[6:7], v[2:3], 1, v[4:5]
	ds_read_b128 v[2:5], v1
	s_waitcnt lgkmcnt(0)
	global_store_dwordx4 v[6:7], v[2:5], off sc1
.LBB0_72:
	s_or_b64 exec, exec, s[2:3]
	s_movk_i32 s2, 0x100
	v_cmp_gt_i32_e32 vcc, s2, v0
	s_and_saveexec_b64 s[2:3], vcc
	s_cbranch_execz .LBB0_63
	v_add_u32_e32 v0, 0x300, v0
	v_ashrrev_i32_e32 v1, 31, v0
	v_lshrrev_b32_e32 v1, 29, v1
	v_add_u32_e32 v1, v0, v1
	v_ashrrev_i32_e32 v4, 3, v1
	v_and_b32_e32 v1, -8, v1
	v_sub_u32_e32 v2, v0, v1
	v_mul_lo_u32 v3, v4, s54
	v_lshlrev_b32_e32 v0, 3, v2
	v_lshl_add_u32 v6, v2, 4, v3
	v_mov_b64_e32 v[2:3], s[0:1]
	s_movk_i32 s0, 0x1600
	v_ashrrev_i32_e32 v1, 31, v0
	v_mad_i64_i32 v[2:3], s[0:1], v4, s0, v[2:3]
	v_lshl_add_u64 v[4:5], v[0:1], 1, v[2:3]
	ds_read_b128 v[0:3], v6
	s_waitcnt lgkmcnt(0)
	global_store_dwordx4 v[4:5], v[0:3], off sc1
	s_branch .LBB0_63

; DI unsigned pk2(float a, float b) { f32x2_t v = {a, b}; bf16x2_t r = __builtin_convertvector(v, bf16x2_t); return __builtin_bit_cast(unsigned, r); }
; DI void phase_rmsnorm(const float* __restrict__ x, const float* __restrict__ wgt, u16* __restrict__ H) {
;     ...
;   for (int row = gw; row < T_; row += nw) {
;     const float4* xr = (const float4*)(x + (long)row * DM);
;     float4 v[4]; float s = 0.f;
; #pragma unroll
;     for (int j = 0; j < 4; ++j) { v[j] = xr[lane + 64 * j]; s += v[j].x * v[j].x + v[j].y * v[j].y + v[j].z * v[j].z + v[j].w * v[j].w; }
;     s = wave_sum(s);
;     float r = rsqrtf(s * (1.f / DM) + EPS);
; #pragma unroll
;     for (int j = 0; j < 4; ++j) {
;       float4 g = ((const float4*)wgt)[lane + 64 * j];
;       uint2 o; o.x = pk2(v[j].x * r * g.x, v[j].y * r * g.y); o.y = pk2(v[j].z * r * g.z, v[j].w * r * g.w);
;       *(uint2*)(H + (long)row * DM + (lane + 64 * j) * 4) = o;
;     }
;   }
.LBB0_78:
	global_load_dwordx4 v[28:31], v[20:21], off nt
	global_load_dwordx4 v[32:35], v[20:21], off offset:1024 nt
	v_add_u32_e32 v16, s40, v16
	s_waitcnt vmcnt(1)
	v_mov_b32_e32 v42, v29
	s_waitcnt vmcnt(0)
	v_mov_b32_e32 v43, v33
	v_mov_b32_e32 v40, v28
	v_mov_b32_e32 v41, v32
	v_pk_mul_f32 v[42:43], v[42:43], v[42:43]
	v_mov_b32_e32 v36, v30
	v_mov_b32_e32 v37, v34
	v_pk_fma_f32 v[40:41], v[40:41], v[40:41], v[42:43]
	v_mov_b32_e32 v38, v31
	v_mov_b32_e32 v39, v35
	v_pk_fma_f32 v[36:37], v[36:37], v[36:37], v[40:41]
	s_nop 0
	v_pk_fma_f32 v[44:45], v[38:39], v[38:39], v[36:37]
	global_load_dwordx4 v[36:39], v[20:21], off offset:2048 nt
	global_load_dwordx4 v[40:43], v[20:21], off offset:3072 nt
	v_add_f32_e32 v17, v44, v45
	v_lshl_add_u64 v[20:21], v[20:21], 0, s[8:9]
	s_waitcnt vmcnt(1)
	v_mov_b32_e32 v52, v37
	s_waitcnt vmcnt(0)
	v_mov_b32_e32 v53, v41
	v_mov_b32_e32 v50, v36
	v_mov_b32_e32 v51, v40
	v_pk_mul_f32 v[52:53], v[52:53], v[52:53]
	v_mov_b32_e32 v46, v38
	v_mov_b32_e32 v47, v42
	v_pk_fma_f32 v[50:51], v[50:51], v[50:51], v[52:53]
	v_mov_b32_e32 v48, v39
	v_mov_b32_e32 v49, v43
	v_pk_fma_f32 v[46:47], v[46:47], v[46:47], v[50:51]
	s_nop 0
	v_pk_fma_f32 v[46:47], v[48:49], v[48:49], v[46:47]
	s_nop 0
	v_add_f32_e32 v17, v17, v46
	v_add_f32_e32 v17, v17, v47
	ds_bpermute_b32 v44, v22, v17
	s_waitcnt lgkmcnt(0)
	v_add_f32_e32 v17, v17, v44
	ds_bpermute_b32 v44, v23, v17
	s_waitcnt lgkmcnt(0)
	v_add_f32_e32 v17, v17, v44
	ds_bpermute_b32 v44, v24, v17
	s_waitcnt lgkmcnt(0)
	v_add_f32_e32 v17, v17, v44
	ds_bpermute_b32 v44, v25, v17
	s_waitcnt lgkmcnt(0)
	v_add_f32_e32 v17, v17, v44
	ds_bpermute_b32 v44, v26, v17
	s_waitcnt lgkmcnt(0)
	v_add_f32_e32 v17, v17, v44
	ds_bpermute_b32 v44, v27, v17
	s_waitcnt lgkmcnt(0)
	v_add_f32_e32 v17, v17, v44
	v_fmamk_f32 v17, v17, 0x3a800000, v164
	v_cmp_gt_f32_e32 vcc, s10, v17
	v_mul_f32_e32 v44, 0x4b800000, v17
	s_nop 0
	v_cndmask_b32_e32 v17, v17, v44, vcc
	v_rsq_f32_e32 v17, v17
	s_nop 0
	v_mul_f32_e32 v44, 0x45800000, v17
	v_cndmask_b32_e32 v44, v17, v44, vcc
	v_pk_mul_f32 v[28:29], v[28:29], v[44:45] op_sel_hi:[1,0]
	v_pk_mul_f32 v[30:31], v[30:31], v[44:45] op_sel_hi:[1,0]
	v_pk_mul_f32 v[28:29], v[0:1], v[28:29]
	v_pk_mul_f32 v[30:31], v[2:3], v[30:31]
	v_cvt_pk_bf16_f32 v28, v28, v29
	v_cvt_pk_bf16_f32 v29, v30, v31
	global_store_dwordx2 v[18:19], v[28:29], off offset:-1024 sc1
	v_pk_mul_f32 v[28:29], v[32:33], v[44:45] op_sel_hi:[1,0]
	v_pk_mul_f32 v[30:31], v[34:35], v[44:45] op_sel_hi:[1,0]
	v_pk_mul_f32 v[28:29], v[4:5], v[28:29]
	v_pk_mul_f32 v[30:31], v[6:7], v[30:31]
	v_cvt_pk_bf16_f32 v28, v28, v29
	v_cvt_pk_bf16_f32 v29, v30, v31
	global_store_dwordx2 v[18:19], v[28:29], off offset:-512 sc1
	v_pk_mul_f32 v[28:29], v[36:37], v[44:45] op_sel_hi:[1,0]
	v_pk_mul_f32 v[30:31], v[38:39], v[44:45] op_sel_hi:[1,0]
	v_pk_mul_f32 v[28:29], v[8:9], v[28:29]
	v_pk_mul_f32 v[30:31], v[10:11], v[30:31]
	v_cvt_pk_bf16_f32 v28, v28, v29
	v_cvt_pk_bf16_f32 v29, v30, v31
	global_store_dwordx2 v[18:19], v[28:29], off sc1
	v_pk_mul_f32 v[28:29], v[40:41], v[44:45] op_sel_hi:[1,0]
	v_pk_mul_f32 v[30:31], v[42:43], v[44:45] op_sel_hi:[1,0]
	v_pk_mul_f32 v[28:29], v[12:13], v[28:29]
	v_pk_mul_f32 v[30:31], v[14:15], v[30:31]
	v_cvt_pk_bf16_f32 v28, v28, v29
	v_cvt_pk_bf16_f32 v29, v30, v31
	v_cmp_lt_i32_e32 vcc, s11, v16
	global_store_dwordx2 v[18:19], v[28:29], off offset:512 sc1
	v_lshl_add_u64 v[18:19], v[18:19], 0, s[6:7]
	s_or_b64 s[2:3], vcc, s[2:3]
	s_andn2_b64 exec, exec, s[2:3]
	s_cbranch_execnz .LBB0_78

;     ...
; #pragma unroll 1
;     for (int kt = 0; kt < nk - 1; ++kt) {
;       asm volatile("s_waitcnt vmcnt(0) lgkmcnt(0)" ::: "memory");
;       __builtin_amdgcn_s_barrier();
;       asm volatile("" ::: "memory");
;       G3_STEP(kt, true)
;     }
.LBB0_107:
	s_lshl_b32 s11, s9, 1
	s_and_b32 s11, s11, 0x8000
	v_lshl_or_b32 v87, v86, 1, s11
	s_waitcnt vmcnt(0) lgkmcnt(0)
	s_barrier
	v_add3_u32 v100, v87, v84, v83
	v_add3_u32 v87, v87, v82, v83
	ds_read_b128 v[88:91], v100
	ds_read_b128 v[92:95], v100 offset:2048
	ds_read_b128 v[96:99], v100 offset:4096
	ds_read_b128 v[100:103], v100 offset:6144
	ds_read_b128 v[104:107], v87 offset:16384
	ds_read_b128 v[108:111], v87 offset:18432
	ds_read_b128 v[112:115], v87 offset:20480
	ds_read_b128 v[116:119], v87 offset:22528
	v_lshl_or_b32 v87, v85, 1, s11
	v_add3_u32 v132, v87, v84, v83
	v_add3_u32 v87, v87, v82, v83
	ds_read_b128 v[120:123], v132
	ds_read_b128 v[124:127], v132 offset:2048
	ds_read_b128 v[128:131], v132 offset:4096
	ds_read_b128 v[132:135], v132 offset:6144
	ds_read_b128 v[136:139], v87 offset:16384
	ds_read_b128 v[140:143], v87 offset:18432
	ds_read_b128 v[144:147], v87 offset:20480
	ds_read_b128 v[148:151], v87 offset:22528
	s_setprio 1
	s_andn2_b32 s11, 0x8000, s10
	s_waitcnt lgkmcnt(11)
	v_mfma_f32_16x16x32_bf16 v[60:63], v[88:91], v[104:107], v[60:63]
	s_add_i32 s11, s1, s11
	v_lshl_add_u64 v[172:173], v[64:65], 0, s[2:3]
	s_mov_b32 m0, s11
	s_nop 0
	global_load_lds_dwordx4 v[172:173], off
	s_waitcnt lgkmcnt(10)
	v_mfma_f32_16x16x32_bf16 v[56:59], v[88:91], v[108:111], v[56:59]
	v_lshl_add_u64 v[152:153], v[78:79], 0, s[2:3]
	v_lshl_add_u64 v[154:155], v[76:77], 0, s[2:3]
	v_lshl_add_u64 v[156:157], v[74:75], 0, s[2:3]
	v_lshl_add_u64 v[158:159], v[72:73], 0, s[2:3]
	v_lshl_add_u64 v[166:167], v[70:71], 0, s[2:3]
	v_lshl_add_u64 v[168:169], v[68:69], 0, s[2:3]
	v_lshl_add_u64 v[170:171], v[66:67], 0, s[2:3]
	s_waitcnt lgkmcnt(9)
	v_mfma_f32_16x16x32_bf16 v[52:55], v[88:91], v[112:115], v[52:55]
	s_add_i32 s12, s11, 0x400
	s_mov_b32 m0, s12
	s_nop 0
	global_load_lds_dwordx4 v[168:169], off
	s_waitcnt lgkmcnt(8)
	v_mfma_f32_16x16x32_bf16 v[48:51], v[88:91], v[116:119], v[48:51]
	v_mfma_f32_16x16x32_bf16 v[44:47], v[92:95], v[104:107], v[44:47]
	s_add_i32 s12, s11, 0x800
	s_mov_b32 m0, s12
	s_nop 0
	global_load_lds_dwordx4 v[156:157], off
	v_mfma_f32_16x16x32_bf16 v[40:43], v[92:95], v[108:111], v[40:43]
	v_mfma_f32_16x16x32_bf16 v[36:39], v[92:95], v[112:115], v[36:39]
	s_add_i32 s12, s11, 0xc00
	s_mov_b32 m0, s12
	s_nop 0
	global_load_lds_dwordx4 v[166:167], off
	v_mfma_f32_16x16x32_bf16 v[32:35], v[92:95], v[116:119], v[32:35]
	v_mfma_f32_16x16x32_bf16 v[28:31], v[96:99], v[104:107], v[28:31]
	s_add_i32 s12, s11, 0x4000
	s_mov_b32 m0, s12
	s_nop 0
	global_load_lds_dwordx4 v[154:155], off
	v_mfma_f32_16x16x32_bf16 v[24:27], v[96:99], v[108:111], v[24:27]
	v_mfma_f32_16x16x32_bf16 v[20:23], v[96:99], v[112:115], v[20:23]
	s_add_i32 s12, s11, 0x4400
	s_mov_b32 m0, s12
	s_nop 0
	global_load_lds_dwordx4 v[158:159], off
	v_mfma_f32_16x16x32_bf16 v[16:19], v[96:99], v[116:119], v[16:19]
	v_mfma_f32_16x16x32_bf16 v[12:15], v[100:103], v[104:107], v[12:15]
	s_add_i32 s12, s11, 0x4800
	s_mov_b32 m0, s12
	s_nop 0
	global_load_lds_dwordx4 v[152:153], off
	v_mfma_f32_16x16x32_bf16 v[8:11], v[100:103], v[108:111], v[8:11]
	v_mfma_f32_16x16x32_bf16 v[4:7], v[100:103], v[112:115], v[4:7]
	s_addk_i32 s11, 0x4c00
	s_mov_b32 m0, s11
	s_nop 0
	global_load_lds_dwordx4 v[170:171], off
	v_mfma_f32_16x16x32_bf16 v[0:3], v[100:103], v[116:119], v[0:3]
	s_waitcnt lgkmcnt(3)
	v_mfma_f32_16x16x32_bf16 v[60:63], v[120:123], v[136:139], v[60:63]
	s_waitcnt lgkmcnt(2)
	v_mfma_f32_16x16x32_bf16 v[56:59], v[120:123], v[140:143], v[56:59]
	s_waitcnt lgkmcnt(1)
	v_mfma_f32_16x16x32_bf16 v[52:55], v[120:123], v[144:147], v[52:55]
	s_waitcnt lgkmcnt(0)
	v_mfma_f32_16x16x32_bf16 v[48:51], v[120:123], v[148:151], v[48:51]
	v_mfma_f32_16x16x32_bf16 v[44:47], v[124:127], v[136:139], v[44:47]
	v_mfma_f32_16x16x32_bf16 v[40:43], v[124:127], v[140:143], v[40:43]
	v_mfma_f32_16x16x32_bf16 v[36:39], v[124:127], v[144:147], v[36:39]
	v_mfma_f32_16x16x32_bf16 v[32:35], v[124:127], v[148:151], v[32:35]
	v_mfma_f32_16x16x32_bf16 v[28:31], v[128:131], v[136:139], v[28:31]
	v_mfma_f32_16x16x32_bf16 v[24:27], v[128:131], v[140:143], v[24:27]
	v_mfma_f32_16x16x32_bf16 v[20:23], v[128:131], v[144:147], v[20:23]
	v_mfma_f32_16x16x32_bf16 v[16:19], v[128:131], v[148:151], v[16:19]
	v_mfma_f32_16x16x32_bf16 v[12:15], v[132:135], v[136:139], v[12:15]
	v_mfma_f32_16x16x32_bf16 v[8:11], v[132:135], v[140:143], v[8:11]
	v_mfma_f32_16x16x32_bf16 v[4:7], v[132:135], v[144:147], v[4:7]
	v_mfma_f32_16x16x32_bf16 v[0:3], v[132:135], v[148:151], v[0:3]
	s_setprio 0
	s_add_i32 s10, s10, 0x8000
	s_add_u32 s2, s2, 0x80
	s_addc_u32 s3, s3, 0
	s_addk_i32 s9, 0x4000
	s_cmpk_lg_i32 s2, 0x780
	s_cbranch_scc1 .LBB0_107
	v_lshlrev_b32_e32 v86, 1, v86
	v_lshlrev_b32_e32 v85, 1, v85
	s_waitcnt vmcnt(0) lgkmcnt(0)
	s_barrier
; DI void resid_tile(const u16* A, int K, const u16* Bt, const float* resid, float* out, int it, u16* sA, u16* sB) {
;     ...
;   float* sC = (float*)sA + w * (32 * 68);
; #pragma unroll
;   for (int hp = 0; hp < 2; ++hp) {
;     __syncthreads();
; #pragma unroll
;     for (int mi2 = 0; mi2 < 2; ++mi2)
; #pragma unroll
;       for (int ni = 0; ni < 4; ++ni)
; #pragma unroll
;         for (int j = 0; j < 4; ++j) sC[(16 * mi2 + 4 * quad + j) * 68 + 16 * ni + r16] = acc[2 * hp + mi2][ni][j];
;     __syncthreads();
; #pragma unroll
;     for (int q = 0; q < 8; ++q) {
;       const int c = lane + 64 * q, row = c >> 4, c4 = (c & 15) * 4;
;       const long o = ((long)mt * 128 + wm * 64 + 32 * hp + row) * DM + nt * 128 + wn * 64 + c4;
;       const float4 rv = *(const float4*)(resid + o);
	v_add3_u32 v76, v86, v84, v83
	v_add3_u32 v98, v86, v82, v83
	v_add3_u32 v84, v85, v84, v83
	v_add3_u32 v126, v85, v82, v83
	ds_read_b128 v[64:67], v76 offset:32768
	ds_read_b128 v[68:71], v76 offset:34816
	ds_read_b128 v[72:75], v76 offset:36864
	ds_read_b128 v[76:79], v76 offset:38912
	ds_read_b128 v[86:89], v98 offset:49152
	ds_read_b128 v[90:93], v98 offset:51200
	ds_read_b128 v[94:97], v98 offset:53248
	ds_read_b128 v[98:101], v98 offset:55296
	ds_read_b128 v[102:105], v84 offset:32768
	ds_read_b128 v[106:109], v84 offset:34816
	ds_read_b128 v[110:113], v84 offset:36864
	ds_read_b128 v[114:117], v84 offset:38912
	ds_read_b128 v[82:85], v126 offset:49152
	ds_read_b128 v[118:121], v126 offset:51200
	ds_read_b128 v[122:125], v126 offset:53248
	ds_read_b128 v[126:129], v126 offset:55296
	s_lshl_b64 s[2:3], s[4:5], 7
	v_and_b32_e32 v130, 15, v80
	s_setprio 1
	s_waitcnt lgkmcnt(11)
	v_mfma_f32_16x16x32_bf16 v[60:63], v[64:67], v[86:89], v[60:63]
	s_waitcnt lgkmcnt(10)
	v_mfma_f32_16x16x32_bf16 v[56:59], v[64:67], v[90:93], v[56:59]
	s_waitcnt lgkmcnt(9)
	v_mfma_f32_16x16x32_bf16 v[52:55], v[64:67], v[94:97], v[52:55]
	s_waitcnt lgkmcnt(8)
	v_mfma_f32_16x16x32_bf16 v[48:51], v[64:67], v[98:101], v[48:51]
	v_mfma_f32_16x16x32_bf16 v[44:47], v[68:71], v[86:89], v[44:47]
	v_mfma_f32_16x16x32_bf16 v[40:43], v[68:71], v[90:93], v[40:43]
	v_mfma_f32_16x16x32_bf16 v[36:39], v[68:71], v[94:97], v[36:39]
	v_mfma_f32_16x16x32_bf16 v[32:35], v[68:71], v[98:101], v[32:35]
	v_mfma_f32_16x16x32_bf16 v[28:31], v[72:75], v[86:89], v[28:31]
	v_mfma_f32_16x16x32_bf16 v[64:67], v[72:75], v[90:93], v[24:27]
	v_mfma_f32_16x16x32_bf16 v[20:23], v[72:75], v[94:97], v[20:23]
	v_mfma_f32_16x16x32_bf16 v[68:71], v[72:75], v[98:101], v[16:19]
	v_mfma_f32_16x16x32_bf16 v[12:15], v[76:79], v[86:89], v[12:15]
	v_mfma_f32_16x16x32_bf16 v[72:75], v[76:79], v[90:93], v[8:11]
	v_mfma_f32_16x16x32_bf16 v[4:7], v[76:79], v[94:97], v[4:7]
	v_mfma_f32_16x16x32_bf16 v[76:79], v[76:79], v[98:101], v[0:3]
	s_waitcnt lgkmcnt(3)
	v_mfma_f32_16x16x32_bf16 v[60:63], v[102:105], v[82:85], v[60:63]
	s_waitcnt lgkmcnt(2)
	v_mfma_f32_16x16x32_bf16 v[56:59], v[102:105], v[118:121], v[56:59]
	s_waitcnt lgkmcnt(1)
	v_mfma_f32_16x16x32_bf16 v[52:55], v[102:105], v[122:125], v[52:55]
	s_waitcnt lgkmcnt(0)
	v_mfma_f32_16x16x32_bf16 v[48:51], v[102:105], v[126:129], v[48:51]
	v_mfma_f32_16x16x32_bf16 v[44:47], v[106:109], v[82:85], v[44:47]
	v_mfma_f32_16x16x32_bf16 v[40:43], v[106:109], v[118:121], v[40:43]
	v_mfma_f32_16x16x32_bf16 v[36:39], v[106:109], v[122:125], v[36:39]
	v_mfma_f32_16x16x32_bf16 v[86:89], v[106:109], v[126:129], v[32:35]
	v_mfma_f32_16x16x32_bf16 v[24:27], v[110:113], v[82:85], v[28:31]
	v_mfma_f32_16x16x32_bf16 v[28:31], v[110:113], v[118:121], v[64:67]
	v_mfma_f32_16x16x32_bf16 v[16:19], v[110:113], v[122:125], v[20:23]
	v_mfma_f32_16x16x32_bf16 v[20:23], v[110:113], v[126:129], v[68:71]
	v_mfma_f32_16x16x32_bf16 v[8:11], v[114:117], v[82:85], v[12:15]
	v_mfma_f32_16x16x32_bf16 v[12:15], v[114:117], v[118:121], v[72:75]
	v_mfma_f32_16x16x32_bf16 v[0:3], v[114:117], v[122:125], v[4:7]
	v_mfma_f32_16x16x32_bf16 v[4:7], v[114:117], v[126:129], v[76:79]
	s_setprio 0
	v_lshrrev_b32_e32 v32, 2, v80
	v_and_b32_e32 v65, 12, v32
	v_lshlrev_b32_e32 v32, 2, v80
	v_mul_lo_u32 v64, v81, s16
	v_and_b32_e32 v67, 60, v32
	v_ashrrev_i32_e32 v32, 1, v80
	s_lshl_b32 s0, s0, 7
	v_and_b32_e32 v34, 64, v80
	v_lshl_or_b32 v66, v130, 2, v64
	v_and_b32_e32 v32, 0xffffffc0, v32
	s_ashr_i32 s1, s0, 31
	v_or3_b32 v34, s0, v34, v67
	s_movk_i32 s0, 0x110
	v_ashrrev_i32_e32 v33, 31, v32
	v_mad_u32_u24 v65, v65, s0, v66
	v_lshl_add_u64 v[32:33], s[2:3], 0, v[32:33]
	v_bfe_u32 v68, v80, 4, 2
	v_lshlrev_b32_e32 v175, 2, v34
	v_or3_b32 v174, v32, v68, 0
	v_lshl_add_u32 v90, v174, 12, v175
	global_load_dwordx4 v[106:109], v90, s[18:19] nt
	v_or3_b32 v174, v32, v68, 4
	v_lshl_add_u32 v91, v174, 12, v175
	global_load_dwordx4 v[110:113], v91, s[18:19] nt
	v_or3_b32 v174, v32, v68, 8
	v_lshl_add_u32 v92, v174, 12, v175
	global_load_dwordx4 v[114:117], v92, s[18:19] nt
	v_or3_b32 v174, v32, v68, 12
	v_lshl_add_u32 v93, v174, 12, v175
	global_load_dwordx4 v[118:121], v93, s[18:19] nt
	v_or3_b32 v174, v32, v68, 16
	v_lshl_add_u32 v94, v174, 12, v175
	global_load_dwordx4 v[122:125], v94, s[18:19] nt
	v_or3_b32 v174, v32, v68, 20
	v_lshl_add_u32 v95, v174, 12, v175
	global_load_dwordx4 v[126:129], v95, s[18:19] nt
	v_or3_b32 v174, v32, v68, 24
	v_lshl_add_u32 v96, v174, 12, v175
	global_load_dwordx4 v[130:133], v96, s[18:19] nt
	v_or3_b32 v174, v32, v68, 28
	v_lshl_add_u32 v97, v174, 12, v175
	global_load_dwordx4 v[134:137], v97, s[18:19] nt
	v_or3_b32 v174, v32, v68, 32
	v_lshl_add_u32 v98, v174, 12, v175
	global_load_dwordx4 v[210:213], v98, s[18:19] nt
	v_or3_b32 v174, v32, v68, 36
	v_lshl_add_u32 v99, v174, 12, v175
	global_load_dwordx4 v[214:217], v99, s[18:19] nt
	v_or3_b32 v174, v32, v68, 40
	v_lshl_add_u32 v100, v174, 12, v175
	global_load_dwordx4 v[218:221], v100, s[18:19] nt
	v_or3_b32 v174, v32, v68, 44
	v_lshl_add_u32 v101, v174, 12, v175
	global_load_dwordx4 v[222:225], v101, s[18:19] nt
	v_or3_b32 v174, v32, v68, 48
	v_lshl_add_u32 v102, v174, 12, v175
	global_load_dwordx4 v[226:229], v102, s[18:19] nt
	v_or3_b32 v174, v32, v68, 52
	v_lshl_add_u32 v103, v174, 12, v175
	global_load_dwordx4 v[230:233], v103, s[18:19] nt
	v_or3_b32 v174, v32, v68, 56
	v_lshl_add_u32 v104, v174, 12, v175
	global_load_dwordx4 v[234:237], v104, s[18:19] nt
	v_or3_b32 v174, v32, v68, 60
	v_lshl_add_u32 v105, v174, 12, v175
	global_load_dwordx4 v[238:241], v105, s[18:19] nt
	s_barrier
; DI void resid_tile(const u16* A, int K, const u16* Bt, const float* resid, float* out, int it, u16* sA, u16* sB) {
;     ...
;   for (int hp = 0; hp < 2; ++hp) {
;     __syncthreads();
; #pragma unroll
;     for (int mi2 = 0; mi2 < 2; ++mi2)
; #pragma unroll
;       for (int ni = 0; ni < 4; ++ni)
; #pragma unroll
;         for (int j = 0; j < 4; ++j) sC[(16 * mi2 + 4 * quad + j) * 68 + 16 * ni + r16] = acc[2 * hp + mi2][ni][j];
;     __syncthreads();
; #pragma unroll
;     for (int q = 0; q < 8; ++q) {
;       const int c = lane + 64 * q, row = c >> 4, c4 = (c & 15) * 4;
;       const long o = ((long)mt * 128 + wm * 64 + 32 * hp + row) * DM + nt * 128 + wn * 64 + c4;
;       const float4 rv = *(const float4*)(resid + o);
;       const f32x4 cv = *(const f32x4*)(sC + row * 68 + c4);
;       *(float4*)(out + o) = make_float4(rv.x + cv[0], rv.y + cv[1], rv.z + cv[2], rv.w + cv[3]);
;     }
;   }
	ds_write2_b32 v65, v60, v56 offset1:16
	ds_write2_b32 v65, v61, v57 offset0:68 offset1:84
	ds_write2_b32 v65, v62, v58 offset0:136 offset1:152
	ds_write2_b32 v65, v63, v59 offset0:204 offset1:220
	ds_write2_b32 v65, v52, v48 offset0:32 offset1:48
	ds_write2_b32 v65, v53, v49 offset0:100 offset1:116
	ds_write2_b32 v65, v54, v50 offset0:168 offset1:184
	ds_write2_b32 v65, v55, v51 offset0:236 offset1:252
	v_add_u32_e32 v54, 0x1000, v65
	v_add_u32_e32 v55, 0x1400, v65
	ds_write2_b32 v54, v44, v40 offset0:64 offset1:80
	ds_write2_b32 v54, v45, v41 offset0:132 offset1:148
	ds_write2_b32 v54, v46, v42 offset0:200 offset1:216
	ds_write2_b32 v55, v47, v43 offset0:12 offset1:28
	ds_write2_b32 v54, v36, v86 offset0:96 offset1:112
	ds_write2_b32 v54, v37, v87 offset0:164 offset1:180
	ds_write2_b32 v54, v38, v88 offset0:232 offset1:248
	ds_write2_b32 v55, v39, v89 offset0:44 offset1:60
	s_waitcnt lgkmcnt(0)
	s_barrier
	v_lshl_or_b32 v40, v67, 2, v64
	v_mad_u32_u24 v57, v68, s0, v40
	ds_read_b128 v[36:39], v57
	ds_read_b128 v[40:43], v57 offset:1088
	ds_read_b128 v[44:47], v57 offset:2176
	ds_read_b128 v[48:51], v57 offset:3264
	ds_read_b128 v[60:63], v57 offset:4352
	ds_read_b128 v[72:75], v57 offset:5440
	ds_read_b128 v[76:79], v57 offset:6528
	ds_read_b128 v[174:177], v57 offset:7616
	s_add_i32 s6, s6, s8
	s_cmp_ge_i32 s6, s7
	s_waitcnt vmcnt(8) lgkmcnt(0)
	v_pk_add_f32 v[36:37], v[106:107], v[36:37]
	v_pk_add_f32 v[38:39], v[108:109], v[38:39]
	global_store_dwordx4 v90, v[36:39], s[68:69] sc1
	v_pk_add_f32 v[40:41], v[110:111], v[40:41]
	v_pk_add_f32 v[42:43], v[112:113], v[42:43]
	global_store_dwordx4 v91, v[40:43], s[68:69] sc1
	v_pk_add_f32 v[44:45], v[114:115], v[44:45]
	v_pk_add_f32 v[46:47], v[116:117], v[46:47]
	global_store_dwordx4 v92, v[44:47], s[68:69] sc1
	v_pk_add_f32 v[48:49], v[118:119], v[48:49]
	v_pk_add_f32 v[50:51], v[120:121], v[50:51]
	global_store_dwordx4 v93, v[48:51], s[68:69] sc1
	v_pk_add_f32 v[60:61], v[122:123], v[60:61]
	v_pk_add_f32 v[62:63], v[124:125], v[62:63]
	global_store_dwordx4 v94, v[60:63], s[68:69] sc1
	v_pk_add_f32 v[72:73], v[126:127], v[72:73]
	v_pk_add_f32 v[74:75], v[128:129], v[74:75]
	global_store_dwordx4 v95, v[72:75], s[68:69] sc1
	v_pk_add_f32 v[76:77], v[130:131], v[76:77]
	v_pk_add_f32 v[78:79], v[132:133], v[78:79]
	global_store_dwordx4 v96, v[76:79], s[68:69] sc1
	v_pk_add_f32 v[174:175], v[134:135], v[174:175]
	v_pk_add_f32 v[176:177], v[136:137], v[176:177]
	global_store_dwordx4 v97, v[174:177], s[68:69] sc1
	s_barrier
	ds_write2_b32 v65, v24, v28 offset1:16
	ds_write2_b32 v65, v25, v29 offset0:68 offset1:84
	ds_write2_b32 v65, v26, v30 offset0:136 offset1:152
	ds_write2_b32 v65, v27, v31 offset0:204 offset1:220
	ds_write2_b32 v65, v16, v20 offset0:32 offset1:48
	ds_write2_b32 v65, v17, v21 offset0:100 offset1:116
	ds_write2_b32 v65, v18, v22 offset0:168 offset1:184
	ds_write2_b32 v65, v19, v23 offset0:236 offset1:252
	ds_write2_b32 v54, v8, v12 offset0:64 offset1:80
	ds_write2_b32 v54, v9, v13 offset0:132 offset1:148
	ds_write2_b32 v54, v10, v14 offset0:200 offset1:216
	ds_write2_b32 v55, v11, v15 offset0:12 offset1:28
	ds_write2_b32 v54, v0, v4 offset0:96 offset1:112
	ds_write2_b32 v54, v1, v5 offset0:164 offset1:180
	ds_write2_b32 v54, v2, v6 offset0:232 offset1:248
	ds_write2_b32 v55, v3, v7 offset0:44 offset1:60
	s_waitcnt lgkmcnt(0)
	s_barrier
	ds_read_b128 v[0:3], v57
	ds_read_b128 v[4:7], v57 offset:1088
	ds_read_b128 v[8:11], v57 offset:2176
	ds_read_b128 v[12:15], v57 offset:3264
	ds_read_b128 v[16:19], v57 offset:4352
	ds_read_b128 v[20:23], v57 offset:5440
	ds_read_b128 v[24:27], v57 offset:6528
	ds_read_b128 v[28:31], v57 offset:7616
	s_waitcnt vmcnt(8) lgkmcnt(0)
	v_pk_add_f32 v[0:1], v[210:211], v[0:1]
	v_pk_add_f32 v[2:3], v[212:213], v[2:3]
	global_store_dwordx4 v98, v[0:3], s[68:69] sc1
	v_pk_add_f32 v[4:5], v[214:215], v[4:5]
	v_pk_add_f32 v[6:7], v[216:217], v[6:7]
	global_store_dwordx4 v99, v[4:7], s[68:69] sc1
	v_pk_add_f32 v[8:9], v[218:219], v[8:9]
	v_pk_add_f32 v[10:11], v[220:221], v[10:11]
	global_store_dwordx4 v100, v[8:11], s[68:69] sc1
	v_pk_add_f32 v[12:13], v[222:223], v[12:13]
	v_pk_add_f32 v[14:15], v[224:225], v[14:15]
	global_store_dwordx4 v101, v[12:15], s[68:69] sc1
	v_pk_add_f32 v[16:17], v[226:227], v[16:17]
	v_pk_add_f32 v[18:19], v[228:229], v[18:19]
	global_store_dwordx4 v102, v[16:19], s[68:69] sc1
	v_pk_add_f32 v[20:21], v[230:231], v[20:21]
	v_pk_add_f32 v[22:23], v[232:233], v[22:23]
	global_store_dwordx4 v103, v[20:23], s[68:69] sc1
	v_pk_add_f32 v[24:25], v[234:235], v[24:25]
	v_pk_add_f32 v[26:27], v[236:237], v[26:27]
	global_store_dwordx4 v104, v[24:27], s[68:69] sc1
	v_pk_add_f32 v[28:29], v[238:239], v[28:29]
	v_pk_add_f32 v[30:31], v[240:241], v[30:31]
	global_store_dwordx4 v105, v[28:31], s[68:69] sc1
	s_cbranch_scc0 .LBB0_106

; template <int NCOLS>
; DI void store_tile_bf16(const u16* sC, u16* gdst, long ld, int rows_valid) {
;     ...
; #pragma unroll
;   for (int q = 0; q < (128 * CPR) / 256; ++q) {
;     const int c = tid + 256 * q, row = c / CPR, ch = c % CPR;
;     if (row < rows_valid) *(uint4*)(gdst + (long)row * ld + ch * 8) = *(const uint4*)(sC + row * LS + ch * 8);
;   }
; DI void merge_tile(const Params& P, int l, int it, u16* sA, u16* sB) {
;     ...
;   __syncthreads();
; #pragma unroll
;   for (int mi = 0; mi < 4; ++mi)
; #pragma unroll
;     for (int ni = 0; ni < 4; ++ni)
; #pragma unroll
;       for (int j = 0; j < 4; ++j) {
;         const unsigned wv = (j < 2) ? outp[mi][ni].x : outp[mi][ni].y;
;         sA[(wm * 64 + 16 * mi + 4 * quad + j) * 136 + wn * 64 + 16 * ni + r16] = (u16)((j & 1) ? (wv >> 16) : (wv & 0xffff));
;       }
;   __syncthreads();
;   store_tile_bf16<128>(sA, MERGED + (long)mt * 128 * DM + nt * 128, DM, 128);
.LBB0_150:
	v_lshrrev_b32_e32 v0, 2, v90
	s_add_u32 s0, s70, s0
	v_and_b32_e32 v0, 12, v0
	s_mov_b32 s5, 0xfffffc0
	s_addc_u32 s1, s71, s1
	v_and_or_b32 v0, v91, s5, v0
	s_movk_i32 s5, 0x110
	s_add_u32 s2, s0, s2
	v_mul_lo_u32 v0, v0, s5
	s_addc_u32 s3, s1, s3
	s_ashr_i32 s5, s4, 31
	s_lshl_b64 s[0:1], s[4:5], 1
	v_and_b32_e32 v1, 0x4f, v90
	s_add_u32 s0, s2, s0
	v_lshl_add_u32 v0, v1, 1, v0
	s_addc_u32 s1, s3, s1
	s_barrier
	ds_write_b16 v0, v119
	ds_write_b16_d16_hi v0, v119 offset:272
	ds_write_b16 v0, v118 offset:544
	ds_write_b16_d16_hi v0, v118 offset:816
	ds_write_b16 v0, v123 offset:32
	ds_write_b16_d16_hi v0, v123 offset:304
	ds_write_b16 v0, v116 offset:576
	ds_write_b16_d16_hi v0, v116 offset:848
	ds_write_b16 v0, v122 offset:64
	ds_write_b16_d16_hi v0, v122 offset:336
	ds_write_b16 v0, v114 offset:608
	ds_write_b16_d16_hi v0, v114 offset:880
	ds_write_b16 v0, v121 offset:96
	ds_write_b16_d16_hi v0, v121 offset:368
	ds_write_b16 v0, v112 offset:640
	ds_write_b16_d16_hi v0, v112 offset:912
	ds_write_b16 v0, v120 offset:4352
	ds_write_b16_d16_hi v0, v120 offset:4624
	ds_write_b16 v0, v110 offset:4896
	ds_write_b16_d16_hi v0, v110 offset:5168
	ds_write_b16 v0, v117 offset:4384
	ds_write_b16_d16_hi v0, v117 offset:4656
	ds_write_b16 v0, v108 offset:4928
	ds_write_b16_d16_hi v0, v108 offset:5200
	ds_write_b16 v0, v115 offset:4416
	ds_write_b16_d16_hi v0, v115 offset:4688
	ds_write_b16 v0, v106 offset:4960
	ds_write_b16_d16_hi v0, v106 offset:5232
	ds_write_b16 v0, v113 offset:4448
	ds_write_b16_d16_hi v0, v113 offset:4720
	ds_write_b16 v0, v104 offset:4992
	ds_write_b16_d16_hi v0, v104 offset:5264
	ds_write_b16 v0, v111 offset:8704
	ds_write_b16_d16_hi v0, v111 offset:8976
	ds_write_b16 v0, v102 offset:9248
	ds_write_b16_d16_hi v0, v102 offset:9520
	ds_write_b16 v0, v109 offset:8736
	ds_write_b16_d16_hi v0, v109 offset:9008
	ds_write_b16 v0, v100 offset:9280
	ds_write_b16_d16_hi v0, v100 offset:9552
	ds_write_b16 v0, v107 offset:8768
	ds_write_b16_d16_hi v0, v107 offset:9040
	ds_write_b16 v0, v98 offset:9312
	ds_write_b16_d16_hi v0, v98 offset:9584
	ds_write_b16 v0, v105 offset:8800
	ds_write_b16_d16_hi v0, v105 offset:9072
	ds_write_b16 v0, v96 offset:9344
	ds_write_b16_d16_hi v0, v96 offset:9616
	ds_write_b16 v0, v103 offset:13056
	ds_write_b16_d16_hi v0, v103 offset:13328
	ds_write_b16 v0, v95 offset:13600
	ds_write_b16_d16_hi v0, v95 offset:13872
	ds_write_b16 v0, v101 offset:13088
	ds_write_b16_d16_hi v0, v101 offset:13360
	ds_write_b16 v0, v94 offset:13632
	ds_write_b16_d16_hi v0, v94 offset:13904
	ds_write_b16 v0, v99 offset:13120
	ds_write_b16_d16_hi v0, v99 offset:13392
	ds_write_b16 v0, v92 offset:13664
	ds_write_b16_d16_hi v0, v92 offset:13936
	ds_write_b16 v0, v97 offset:13152
	ds_write_b16_d16_hi v0, v97 offset:13424
	ds_write_b16 v0, v93 offset:13696
	ds_write_b16_d16_hi v0, v93 offset:13968
	s_add_u32 s0, s0, 0x13000000
	v_mov_b32_e32 v0, v160
	s_movk_i32 s2, 0x800
	s_waitcnt lgkmcnt(0)
	s_barrier
	s_addc_u32 s1, s1, 0
	s_nop 0
	v_cmp_gt_i32_e32 vcc, s2, v0
	s_and_saveexec_b64 s[2:3], vcc
	s_cbranch_execz .LBB0_152
	v_ashrrev_i32_e32 v1, 31, v0
	v_lshrrev_b32_e32 v1, 28, v1
	v_add_u32_e32 v1, v0, v1
	v_ashrrev_i32_e32 v2, 4, v1
	v_and_b32_e32 v1, -16, v1
	s_movk_i32 s4, 0x110
	v_sub_u32_e32 v1, v0, v1
	v_mul_lo_u32 v3, v2, s4
	v_lshlrev_b32_e32 v4, 3, v1
	v_lshl_add_u32 v1, v1, 4, v3
	v_ashrrev_i32_e32 v3, 31, v2
	v_lshlrev_b64 v[2:3], 11, v[2:3]
	v_ashrrev_i32_e32 v5, 31, v4
	v_lshl_add_u64 v[2:3], s[0:1], 0, v[2:3]
	v_lshl_add_u64 v[6:7], v[4:5], 1, v[2:3]
	ds_read_b128 v[2:5], v1
	s_waitcnt lgkmcnt(0)
	global_store_dwordx4 v[6:7], v[2:5], off sc1
.LBB0_152:
	s_or_b64 exec, exec, s[2:3]
	s_movk_i32 s2, 0x700
	v_cmp_gt_i32_e32 vcc, s2, v0
	s_and_saveexec_b64 s[2:3], vcc
	s_cbranch_execz .LBB0_154
	v_add_u32_e32 v1, 0x100, v0
	v_ashrrev_i32_e32 v2, 31, v1
	v_lshrrev_b32_e32 v2, 28, v2
	v_add_u32_e32 v3, v1, v2
	v_ashrrev_i32_e32 v2, 4, v3
	v_and_b32_e32 v3, -16, v3
	s_movk_i32 s4, 0x110
	v_sub_u32_e32 v1, v1, v3
	v_mul_lo_u32 v3, v2, s4
	v_lshlrev_b32_e32 v4, 3, v1
	v_lshl_add_u32 v1, v1, 4, v3
	v_ashrrev_i32_e32 v3, 31, v2
	v_lshlrev_b64 v[2:3], 11, v[2:3]
	v_ashrrev_i32_e32 v5, 31, v4
	v_lshl_add_u64 v[2:3], s[0:1], 0, v[2:3]
	v_lshl_add_u64 v[6:7], v[4:5], 1, v[2:3]
	ds_read_b128 v[2:5], v1
	s_waitcnt lgkmcnt(0)
	global_store_dwordx4 v[6:7], v[2:5], off sc1
; template <int NCOLS>
; DI void store_tile_bf16(const u16* sC, u16* gdst, long ld, int rows_valid) {
;     ...
; #pragma unroll
;   for (int q = 0; q < (128 * CPR) / 256; ++q) {
;     const int c = tid + 256 * q, row = c / CPR, ch = c % CPR;
;     if (row < rows_valid) *(uint4*)(gdst + (long)row * ld + ch * 8) = *(const uint4*)(sC + row * LS + ch * 8);
;   }
.LBB0_154:
	s_or_b64 exec, exec, s[2:3]
	s_movk_i32 s2, 0x600
	v_cmp_gt_i32_e32 vcc, s2, v0
	s_and_saveexec_b64 s[2:3], vcc
	s_cbranch_execz .LBB0_156
	v_add_u32_e32 v1, 0x200, v0
	v_ashrrev_i32_e32 v2, 31, v1
	v_lshrrev_b32_e32 v2, 28, v2
	v_add_u32_e32 v3, v1, v2
	v_ashrrev_i32_e32 v2, 4, v3
	v_and_b32_e32 v3, -16, v3
	s_movk_i32 s4, 0x110
	v_sub_u32_e32 v1, v1, v3
	v_mul_lo_u32 v3, v2, s4
	v_lshlrev_b32_e32 v4, 3, v1
	v_lshl_add_u32 v1, v1, 4, v3
	v_ashrrev_i32_e32 v3, 31, v2
	v_lshlrev_b64 v[2:3], 11, v[2:3]
	v_ashrrev_i32_e32 v5, 31, v4
	v_lshl_add_u64 v[2:3], s[0:1], 0, v[2:3]
	v_lshl_add_u64 v[6:7], v[4:5], 1, v[2:3]
	ds_read_b128 v[2:5], v1
	s_waitcnt lgkmcnt(0)
	global_store_dwordx4 v[6:7], v[2:5], off sc1
.LBB0_156:
	s_or_b64 exec, exec, s[2:3]
	s_movk_i32 s2, 0x500
	v_cmp_gt_i32_e32 vcc, s2, v0
	s_and_saveexec_b64 s[2:3], vcc
	s_cbranch_execz .LBB0_158
	v_add_u32_e32 v1, 0x300, v0
	v_ashrrev_i32_e32 v2, 31, v1
	v_lshrrev_b32_e32 v2, 28, v2
	v_add_u32_e32 v3, v1, v2
	v_ashrrev_i32_e32 v2, 4, v3
	v_and_b32_e32 v3, -16, v3
	s_movk_i32 s4, 0x110
	v_sub_u32_e32 v1, v1, v3
	v_mul_lo_u32 v3, v2, s4
	v_lshlrev_b32_e32 v4, 3, v1
	v_lshl_add_u32 v1, v1, 4, v3
	v_ashrrev_i32_e32 v3, 31, v2
	v_lshlrev_b64 v[2:3], 11, v[2:3]
	v_ashrrev_i32_e32 v5, 31, v4
	v_lshl_add_u64 v[2:3], s[0:1], 0, v[2:3]
	v_lshl_add_u64 v[6:7], v[4:5], 1, v[2:3]
	ds_read_b128 v[2:5], v1
	s_waitcnt lgkmcnt(0)
	global_store_dwordx4 v[6:7], v[2:5], off sc1
.LBB0_158:
	s_or_b64 exec, exec, s[2:3]
	s_movk_i32 s2, 0x400
	v_cmp_gt_i32_e32 vcc, s2, v0
	s_and_saveexec_b64 s[2:3], vcc
	s_cbranch_execz .LBB0_160
	v_add_u32_e32 v1, 0x400, v0
	v_ashrrev_i32_e32 v2, 31, v1
	v_lshrrev_b32_e32 v2, 28, v2
	v_add_u32_e32 v3, v1, v2
	v_ashrrev_i32_e32 v2, 4, v3
	v_and_b32_e32 v3, -16, v3
	s_movk_i32 s4, 0x110
	v_sub_u32_e32 v1, v1, v3
	v_mul_lo_u32 v3, v2, s4
	v_lshlrev_b32_e32 v4, 3, v1
	v_lshl_add_u32 v1, v1, 4, v3
	v_ashrrev_i32_e32 v3, 31, v2
	v_lshlrev_b64 v[2:3], 11, v[2:3]
	v_ashrrev_i32_e32 v5, 31, v4
	v_lshl_add_u64 v[2:3], s[0:1], 0, v[2:3]
	v_lshl_add_u64 v[6:7], v[4:5], 1, v[2:3]
	ds_read_b128 v[2:5], v1
	s_waitcnt lgkmcnt(0)
	global_store_dwordx4 v[6:7], v[2:5], off sc1
.LBB0_160:
	s_or_b64 exec, exec, s[2:3]
	s_movk_i32 s2, 0x300
	v_cmp_gt_i32_e32 vcc, s2, v0
	s_and_saveexec_b64 s[2:3], vcc
	s_cbranch_execz .LBB0_162
	v_add_u32_e32 v1, 0x500, v0
	v_ashrrev_i32_e32 v2, 31, v1
	v_lshrrev_b32_e32 v2, 28, v2
	v_add_u32_e32 v3, v1, v2
	v_ashrrev_i32_e32 v2, 4, v3
	v_and_b32_e32 v3, -16, v3
	s_movk_i32 s4, 0x110
	v_sub_u32_e32 v1, v1, v3
	v_mul_lo_u32 v3, v2, s4
	v_lshlrev_b32_e32 v4, 3, v1
	v_lshl_add_u32 v1, v1, 4, v3
	v_ashrrev_i32_e32 v3, 31, v2
	v_lshlrev_b64 v[2:3], 11, v[2:3]
	v_ashrrev_i32_e32 v5, 31, v4
	v_lshl_add_u64 v[2:3], s[0:1], 0, v[2:3]
	v_lshl_add_u64 v[6:7], v[4:5], 1, v[2:3]
	ds_read_b128 v[2:5], v1
	s_waitcnt lgkmcnt(0)
	global_store_dwordx4 v[6:7], v[2:5], off sc1
.LBB0_162:
	s_or_b64 exec, exec, s[2:3]
	s_movk_i32 s2, 0x200
	v_cmp_gt_i32_e32 vcc, s2, v0
	s_and_saveexec_b64 s[2:3], vcc
	s_cbranch_execz .LBB0_164
	v_add_u32_e32 v1, 0x600, v0
	v_ashrrev_i32_e32 v2, 31, v1
	v_lshrrev_b32_e32 v2, 28, v2
	v_add_u32_e32 v3, v1, v2
	v_ashrrev_i32_e32 v2, 4, v3
	v_and_b32_e32 v3, -16, v3
	s_movk_i32 s4, 0x110
	v_sub_u32_e32 v1, v1, v3
	v_mul_lo_u32 v3, v2, s4
	v_lshlrev_b32_e32 v4, 3, v1
	v_lshl_add_u32 v1, v1, 4, v3
	v_ashrrev_i32_e32 v3, 31, v2
	v_lshlrev_b64 v[2:3], 11, v[2:3]
	v_ashrrev_i32_e32 v5, 31, v4
	v_lshl_add_u64 v[2:3], s[0:1], 0, v[2:3]
	v_lshl_add_u64 v[6:7], v[4:5], 1, v[2:3]
	ds_read_b128 v[2:5], v1
	s_waitcnt lgkmcnt(0)
	global_store_dwordx4 v[6:7], v[2:5], off sc1
.LBB0_164:
	s_or_b64 exec, exec, s[2:3]
	s_movk_i32 s2, 0x100
	v_cmp_gt_i32_e32 vcc, s2, v0
	s_and_saveexec_b64 s[2:3], vcc
	s_cbranch_execz .LBB0_133
	v_add_u32_e32 v1, 0x700, v0
	v_ashrrev_i32_e32 v0, 31, v1
	v_lshrrev_b32_e32 v0, 28, v0
	v_add_u32_e32 v2, v1, v0
	v_ashrrev_i32_e32 v0, 4, v2
	v_and_b32_e32 v2, -16, v2
	s_movk_i32 s4, 0x110
	v_sub_u32_e32 v1, v1, v2
	v_mul_lo_u32 v4, v0, s4
	v_lshlrev_b32_e32 v2, 3, v1
	v_lshl_add_u32 v6, v1, 4, v4
	v_ashrrev_i32_e32 v1, 31, v0
	v_lshlrev_b64 v[0:1], 11, v[0:1]
	v_ashrrev_i32_e32 v3, 31, v2
	v_lshl_add_u64 v[0:1], s[0:1], 0, v[0:1]
	v_lshl_add_u64 v[4:5], v[2:3], 1, v[0:1]
	ds_read_b128 v[0:3], v6
	s_waitcnt lgkmcnt(0)
	global_store_dwordx4 v[4:5], v[0:3], off sc1
	s_branch .LBB0_133

;     ...
; #pragma unroll 1
;     for (int kt = 0; kt < nk - 1; ++kt) {
;       asm volatile("s_waitcnt vmcnt(0) lgkmcnt(0)" ::: "memory");
;       __builtin_amdgcn_s_barrier();
;       asm volatile("" ::: "memory");
;       G3_STEP(kt, true)
;     }
.LBB0_660:
	s_lshl_b32 s12, s3, 1
	s_and_b32 s12, s12, 0x8000
	v_lshl_or_b32 v87, v86, 1, s12
	s_waitcnt vmcnt(0) lgkmcnt(0)
	s_barrier
	v_add3_u32 v100, v87, v84, v83
	v_add3_u32 v87, v87, v82, v83
	ds_read_b128 v[88:91], v100
	ds_read_b128 v[92:95], v100 offset:2048
	ds_read_b128 v[96:99], v100 offset:4096
	ds_read_b128 v[100:103], v100 offset:6144
	ds_read_b128 v[104:107], v87 offset:16384
	ds_read_b128 v[108:111], v87 offset:18432
	ds_read_b128 v[112:115], v87 offset:20480
	ds_read_b128 v[116:119], v87 offset:22528
	v_lshl_or_b32 v87, v85, 1, s12
	v_add3_u32 v132, v87, v84, v83
	v_add3_u32 v87, v87, v82, v83
	ds_read_b128 v[120:123], v132
	ds_read_b128 v[124:127], v132 offset:2048
	ds_read_b128 v[128:131], v132 offset:4096
	ds_read_b128 v[132:135], v132 offset:6144
	ds_read_b128 v[136:139], v87 offset:16384
	ds_read_b128 v[140:143], v87 offset:18432
	ds_read_b128 v[144:147], v87 offset:20480
	ds_read_b128 v[148:151], v87 offset:22528
	s_setprio 1
	s_andn2_b32 s12, 0x8000, s11
	s_waitcnt lgkmcnt(11)
	v_mfma_f32_16x16x32_bf16 v[60:63], v[88:91], v[104:107], v[60:63]
	s_add_i32 s12, s1, s12
	v_lshl_add_u64 v[172:173], v[64:65], 0, s[6:7]
	s_mov_b32 m0, s12
	s_nop 0
	global_load_lds_dwordx4 v[172:173], off
	s_waitcnt lgkmcnt(10)
	v_mfma_f32_16x16x32_bf16 v[56:59], v[88:91], v[108:111], v[56:59]
	v_lshl_add_u64 v[152:153], v[78:79], 0, s[6:7]
	v_lshl_add_u64 v[154:155], v[76:77], 0, s[6:7]
	v_lshl_add_u64 v[156:157], v[74:75], 0, s[6:7]
	v_lshl_add_u64 v[158:159], v[72:73], 0, s[6:7]
	v_lshl_add_u64 v[166:167], v[70:71], 0, s[6:7]
	v_lshl_add_u64 v[168:169], v[68:69], 0, s[6:7]
	v_lshl_add_u64 v[170:171], v[66:67], 0, s[6:7]
	s_waitcnt lgkmcnt(9)
	v_mfma_f32_16x16x32_bf16 v[52:55], v[88:91], v[112:115], v[52:55]
	s_add_i32 s13, s12, 0x400
	s_mov_b32 m0, s13
	s_nop 0
	global_load_lds_dwordx4 v[168:169], off
	s_waitcnt lgkmcnt(8)
	v_mfma_f32_16x16x32_bf16 v[48:51], v[88:91], v[116:119], v[48:51]
	v_mfma_f32_16x16x32_bf16 v[44:47], v[92:95], v[104:107], v[44:47]
	s_add_i32 s13, s12, 0x800
	s_mov_b32 m0, s13
	s_nop 0
	global_load_lds_dwordx4 v[156:157], off
	v_mfma_f32_16x16x32_bf16 v[40:43], v[92:95], v[108:111], v[40:43]
	v_mfma_f32_16x16x32_bf16 v[36:39], v[92:95], v[112:115], v[36:39]
	s_add_i32 s13, s12, 0xc00
	s_mov_b32 m0, s13
	s_nop 0
	global_load_lds_dwordx4 v[166:167], off
	v_mfma_f32_16x16x32_bf16 v[32:35], v[92:95], v[116:119], v[32:35]
	v_mfma_f32_16x16x32_bf16 v[28:31], v[96:99], v[104:107], v[28:31]
	s_add_i32 s13, s12, 0x4000
	s_mov_b32 m0, s13
	s_nop 0
	global_load_lds_dwordx4 v[154:155], off
	v_mfma_f32_16x16x32_bf16 v[24:27], v[96:99], v[108:111], v[24:27]
	v_mfma_f32_16x16x32_bf16 v[20:23], v[96:99], v[112:115], v[20:23]
	s_add_i32 s13, s12, 0x4400
	s_mov_b32 m0, s13
	s_nop 0
	global_load_lds_dwordx4 v[158:159], off
	v_mfma_f32_16x16x32_bf16 v[16:19], v[96:99], v[116:119], v[16:19]
	v_mfma_f32_16x16x32_bf16 v[12:15], v[100:103], v[104:107], v[12:15]
	s_add_i32 s13, s12, 0x4800
	s_mov_b32 m0, s13
	s_nop 0
	global_load_lds_dwordx4 v[152:153], off
	v_mfma_f32_16x16x32_bf16 v[8:11], v[100:103], v[108:111], v[8:11]
	v_mfma_f32_16x16x32_bf16 v[4:7], v[100:103], v[112:115], v[4:7]
	s_addk_i32 s12, 0x4c00
	s_mov_b32 m0, s12
	s_nop 0
	global_load_lds_dwordx4 v[170:171], off
	v_mfma_f32_16x16x32_bf16 v[0:3], v[100:103], v[116:119], v[0:3]
	s_waitcnt lgkmcnt(3)
	v_mfma_f32_16x16x32_bf16 v[60:63], v[120:123], v[136:139], v[60:63]
	s_waitcnt lgkmcnt(2)
	v_mfma_f32_16x16x32_bf16 v[56:59], v[120:123], v[140:143], v[56:59]
	s_waitcnt lgkmcnt(1)
	v_mfma_f32_16x16x32_bf16 v[52:55], v[120:123], v[144:147], v[52:55]
	s_waitcnt lgkmcnt(0)
	v_mfma_f32_16x16x32_bf16 v[48:51], v[120:123], v[148:151], v[48:51]
	v_mfma_f32_16x16x32_bf16 v[44:47], v[124:127], v[136:139], v[44:47]
	v_mfma_f32_16x16x32_bf16 v[40:43], v[124:127], v[140:143], v[40:43]
	v_mfma_f32_16x16x32_bf16 v[36:39], v[124:127], v[144:147], v[36:39]
	v_mfma_f32_16x16x32_bf16 v[32:35], v[124:127], v[148:151], v[32:35]
	v_mfma_f32_16x16x32_bf16 v[28:31], v[128:131], v[136:139], v[28:31]
	v_mfma_f32_16x16x32_bf16 v[24:27], v[128:131], v[140:143], v[24:27]
	v_mfma_f32_16x16x32_bf16 v[20:23], v[128:131], v[144:147], v[20:23]
	v_mfma_f32_16x16x32_bf16 v[16:19], v[128:131], v[148:151], v[16:19]
	v_mfma_f32_16x16x32_bf16 v[12:15], v[132:135], v[136:139], v[12:15]
	v_mfma_f32_16x16x32_bf16 v[8:11], v[132:135], v[140:143], v[8:11]
	v_mfma_f32_16x16x32_bf16 v[4:7], v[132:135], v[144:147], v[4:7]
	v_mfma_f32_16x16x32_bf16 v[0:3], v[132:135], v[148:151], v[0:3]
	s_setprio 0
	s_add_i32 s11, s11, 0x8000
	s_add_u32 s6, s6, 0x80
	s_addc_u32 s7, s7, 0
	s_addk_i32 s3, 0x4000
	s_cmpk_lg_i32 s6, 0x780
	s_cbranch_scc1 .LBB0_660
	v_lshlrev_b32_e32 v86, 1, v86
	v_lshlrev_b32_e32 v85, 1, v85
	s_waitcnt vmcnt(0) lgkmcnt(0)
	s_barrier
; DI void inproj_tile(const Params& P, int l, int it, u16* sA, u16* sB) {
;     ...
;   __syncthreads();
; #pragma unroll
;   for (int mi = 0; mi < 4; ++mi)
; #pragma unroll
;     for (int ni = 0; ni < 4; ++ni)
; #pragma unroll
;       for (int j = 0; j < 4; ++j) sA[(wm * 64 + 16 * mi + 4 * quad + j) * 136 + wn * 64 + 16 * ni + r16] = f2bf(acc[mi][ni][j]);
	v_add3_u32 v76, v86, v84, v83
	v_add3_u32 v98, v86, v82, v83
	v_add3_u32 v84, v85, v84, v83
	v_add3_u32 v126, v85, v82, v83
	ds_read_b128 v[64:67], v76 offset:32768
	ds_read_b128 v[68:71], v76 offset:34816
	ds_read_b128 v[72:75], v76 offset:36864
	ds_read_b128 v[76:79], v76 offset:38912
	ds_read_b128 v[86:89], v98 offset:49152
	ds_read_b128 v[90:93], v98 offset:51200
	ds_read_b128 v[94:97], v98 offset:53248
	ds_read_b128 v[98:101], v98 offset:55296
	ds_read_b128 v[102:105], v84 offset:32768
	ds_read_b128 v[106:109], v84 offset:34816
	ds_read_b128 v[110:113], v84 offset:36864
	ds_read_b128 v[114:117], v84 offset:38912
	ds_read_b128 v[82:85], v126 offset:49152
	ds_read_b128 v[118:121], v126 offset:51200
	ds_read_b128 v[122:125], v126 offset:53248
	ds_read_b128 v[126:129], v126 offset:55296
	s_setprio 1
	s_waitcnt lgkmcnt(11)
	v_mfma_f32_16x16x32_bf16 v[60:63], v[64:67], v[86:89], v[60:63]
	s_waitcnt lgkmcnt(10)
	v_mfma_f32_16x16x32_bf16 v[56:59], v[64:67], v[90:93], v[56:59]
	s_waitcnt lgkmcnt(9)
	v_mfma_f32_16x16x32_bf16 v[52:55], v[64:67], v[94:97], v[52:55]
	s_waitcnt lgkmcnt(8)
	v_mfma_f32_16x16x32_bf16 v[48:51], v[64:67], v[98:101], v[48:51]
	v_mfma_f32_16x16x32_bf16 v[44:47], v[68:71], v[86:89], v[44:47]
	v_mfma_f32_16x16x32_bf16 v[40:43], v[68:71], v[90:93], v[40:43]
	v_mfma_f32_16x16x32_bf16 v[36:39], v[68:71], v[94:97], v[36:39]
	v_mfma_f32_16x16x32_bf16 v[32:35], v[68:71], v[98:101], v[32:35]
	v_mfma_f32_16x16x32_bf16 v[28:31], v[72:75], v[86:89], v[28:31]
	v_mfma_f32_16x16x32_bf16 v[24:27], v[72:75], v[90:93], v[24:27]
	v_mfma_f32_16x16x32_bf16 v[20:23], v[72:75], v[94:97], v[20:23]
	v_mfma_f32_16x16x32_bf16 v[16:19], v[72:75], v[98:101], v[16:19]
	v_mfma_f32_16x16x32_bf16 v[12:15], v[76:79], v[86:89], v[12:15]
	v_mfma_f32_16x16x32_bf16 v[8:11], v[76:79], v[90:93], v[8:11]
	v_mfma_f32_16x16x32_bf16 v[0:3], v[76:79], v[98:101], v[0:3]
	v_mfma_f32_16x16x32_bf16 v[4:7], v[76:79], v[94:97], v[4:7]
	s_waitcnt lgkmcnt(0)
	v_mfma_f32_16x16x32_bf16 v[0:3], v[114:117], v[126:129], v[0:3]
	v_mfma_f32_16x16x32_bf16 v[60:63], v[102:105], v[82:85], v[60:63]
	v_mfma_f32_16x16x32_bf16 v[56:59], v[102:105], v[118:121], v[56:59]
	v_mfma_f32_16x16x32_bf16 v[52:55], v[102:105], v[122:125], v[52:55]
	v_mfma_f32_16x16x32_bf16 v[48:51], v[102:105], v[126:129], v[48:51]
	v_mfma_f32_16x16x32_bf16 v[44:47], v[106:109], v[82:85], v[44:47]
	v_mfma_f32_16x16x32_bf16 v[40:43], v[106:109], v[118:121], v[40:43]
	v_mfma_f32_16x16x32_bf16 v[36:39], v[106:109], v[122:125], v[36:39]
	v_mfma_f32_16x16x32_bf16 v[32:35], v[106:109], v[126:129], v[32:35]
	v_mfma_f32_16x16x32_bf16 v[28:31], v[110:113], v[82:85], v[28:31]
	v_mfma_f32_16x16x32_bf16 v[24:27], v[110:113], v[118:121], v[24:27]
	v_mfma_f32_16x16x32_bf16 v[20:23], v[110:113], v[122:125], v[20:23]
	v_mfma_f32_16x16x32_bf16 v[16:19], v[110:113], v[126:129], v[16:19]
	v_mfma_f32_16x16x32_bf16 v[12:15], v[114:117], v[82:85], v[12:15]
	v_mfma_f32_16x16x32_bf16 v[8:11], v[114:117], v[118:121], v[8:11]
	v_mfma_f32_16x16x32_bf16 v[4:7], v[114:117], v[122:125], v[4:7]
	s_setprio 0
	v_lshrrev_b32_e32 v64, 2, v80
	v_and_b32_e32 v64, 12, v64
	s_mov_b32 s1, 0xfffffc0
	v_and_or_b32 v64, v81, s1, v64
	s_movk_i32 s1, 0x110
	v_and_b32_e32 v65, 0x4f, v80
	v_mul_lo_u32 v64, v64, s1
	v_cvt_pk_bf16_f32 v60, v60, s0
	v_lshl_add_u32 v64, v65, 1, v64
	v_cvt_pk_bf16_f32 v56, v56, s0
	v_cvt_pk_bf16_f32 v52, v52, s0
	v_cvt_pk_bf16_f32 v48, v48, s0
	v_cvt_pk_bf16_f32 v44, v44, s0
	v_cvt_pk_bf16_f32 v40, v40, s0
	v_cvt_pk_bf16_f32 v36, v36, s0
	v_cvt_pk_bf16_f32 v32, v32, s0
	v_cvt_pk_bf16_f32 v28, v28, s0
	v_cvt_pk_bf16_f32 v24, v24, s0
	v_cvt_pk_bf16_f32 v20, v20, s0
	v_cvt_pk_bf16_f32 v16, v16, s0
	v_cvt_pk_bf16_f32 v12, v12, s0
	v_cvt_pk_bf16_f32 v8, v8, s0
	v_cvt_pk_bf16_f32 v4, v4, s0
	v_cvt_pk_bf16_f32 v0, v0, s0
	s_add_u32 s1, s70, s4
	s_barrier
	ds_write_b16 v64, v60
	v_cvt_pk_bf16_f32 v60, v61, s0
	ds_write_b16 v64, v56 offset:32
	v_cvt_pk_bf16_f32 v56, v57, s0
	ds_write_b16 v64, v52 offset:64
	v_cvt_pk_bf16_f32 v52, v53, s0
	ds_write_b16 v64, v48 offset:96
	v_cvt_pk_bf16_f32 v48, v49, s0
	ds_write_b16 v64, v44 offset:4352
	v_cvt_pk_bf16_f32 v44, v45, s0
	ds_write_b16 v64, v40 offset:4384
	v_cvt_pk_bf16_f32 v40, v41, s0
	ds_write_b16 v64, v36 offset:4416
	v_cvt_pk_bf16_f32 v36, v37, s0
	ds_write_b16 v64, v32 offset:4448
	v_cvt_pk_bf16_f32 v32, v33, s0
	ds_write_b16 v64, v28 offset:8704
	v_cvt_pk_bf16_f32 v28, v29, s0
	ds_write_b16 v64, v24 offset:8736
	v_cvt_pk_bf16_f32 v24, v25, s0
	ds_write_b16 v64, v20 offset:8768
	v_cvt_pk_bf16_f32 v20, v21, s0
	ds_write_b16 v64, v16 offset:8800
	v_cvt_pk_bf16_f32 v16, v17, s0
	ds_write_b16 v64, v12 offset:13056
	v_cvt_pk_bf16_f32 v12, v13, s0
	ds_write_b16 v64, v8 offset:13088
	v_cvt_pk_bf16_f32 v8, v9, s0
	ds_write_b16 v64, v4 offset:13120
	v_cvt_pk_bf16_f32 v4, v5, s0
	ds_write_b16 v64, v0 offset:13152
	v_cvt_pk_bf16_f32 v0, v1, s0
	s_addc_u32 s3, s71, s5
	s_mul_hi_i32 s4, s2, 0xb0000
	s_mul_i32 s2, s2, 0xb0000
	ds_write_b16 v64, v60 offset:272
	v_cvt_pk_bf16_f32 v60, v62, s0
	ds_write_b16 v64, v56 offset:304
	v_cvt_pk_bf16_f32 v56, v58, s0
	ds_write_b16 v64, v52 offset:336
	v_cvt_pk_bf16_f32 v52, v54, s0
	ds_write_b16 v64, v48 offset:368
	v_cvt_pk_bf16_f32 v48, v50, s0
	ds_write_b16 v64, v44 offset:4624
	v_cvt_pk_bf16_f32 v44, v46, s0
	ds_write_b16 v64, v40 offset:4656
	v_cvt_pk_bf16_f32 v40, v42, s0
	ds_write_b16 v64, v36 offset:4688
	v_cvt_pk_bf16_f32 v36, v38, s0
	ds_write_b16 v64, v32 offset:4720
	v_cvt_pk_bf16_f32 v32, v34, s0
	ds_write_b16 v64, v28 offset:8976
	v_cvt_pk_bf16_f32 v28, v30, s0
	ds_write_b16 v64, v24 offset:9008
	v_cvt_pk_bf16_f32 v24, v26, s0
	ds_write_b16 v64, v20 offset:9040
; template <int NCOLS>
; DI void store_tile_bf16(const u16* sC, u16* gdst, long ld, int rows_valid) {
;     ...
; #pragma unroll
;   for (int q = 0; q < (128 * CPR) / 256; ++q) {
;     const int c = tid + 256 * q, row = c / CPR, ch = c % CPR;
;     if (row < rows_valid) *(uint4*)(gdst + (long)row * ld + ch * 8) = *(const uint4*)(sC + row * LS + ch * 8);
;   }
; DI void inproj_tile(const Params& P, int l, int it, u16* sA, u16* sB) {
;     ...
;   __syncthreads();
; #pragma unroll
;   for (int mi = 0; mi < 4; ++mi)
; #pragma unroll
;     for (int ni = 0; ni < 4; ++ni)
; #pragma unroll
;       for (int j = 0; j < 4; ++j) sA[(wm * 64 + 16 * mi + 4 * quad + j) * 136 + wn * 64 + 16 * ni + r16] = f2bf(acc[mi][ni][j]);
;   __syncthreads();
;   store_tile_bf16<128>(sA, PROJ + (long)mt * 128 * PW + nt * 128, PW, 128);
	v_cvt_pk_bf16_f32 v20, v22, s0
	ds_write_b16 v64, v16 offset:9072
	v_cvt_pk_bf16_f32 v16, v18, s0
	ds_write_b16 v64, v12 offset:13328
	v_cvt_pk_bf16_f32 v12, v14, s0
	ds_write_b16 v64, v8 offset:13360
	v_cvt_pk_bf16_f32 v8, v10, s0
	ds_write_b16 v64, v4 offset:13392
	v_cvt_pk_bf16_f32 v4, v6, s0
	ds_write_b16 v64, v0 offset:13424
	v_cvt_pk_bf16_f32 v0, v2, s0
	s_add_u32 s2, s1, s2
	ds_write_b16 v64, v60 offset:544
	v_cvt_pk_bf16_f32 v60, v63, s0
	ds_write_b16 v64, v56 offset:576
	v_cvt_pk_bf16_f32 v56, v59, s0
	ds_write_b16 v64, v52 offset:608
	v_cvt_pk_bf16_f32 v52, v55, s0
	ds_write_b16 v64, v48 offset:640
	v_cvt_pk_bf16_f32 v48, v51, s0
	ds_write_b16 v64, v44 offset:4896
	v_cvt_pk_bf16_f32 v44, v47, s0
	ds_write_b16 v64, v40 offset:4928
	v_cvt_pk_bf16_f32 v40, v43, s0
	ds_write_b16 v64, v36 offset:4960
	v_cvt_pk_bf16_f32 v36, v39, s0
	ds_write_b16 v64, v32 offset:4992
	v_cvt_pk_bf16_f32 v32, v35, s0
	ds_write_b16 v64, v28 offset:9248
	v_cvt_pk_bf16_f32 v28, v31, s0
	ds_write_b16 v64, v24 offset:9280
	v_cvt_pk_bf16_f32 v24, v27, s0
	ds_write_b16 v64, v20 offset:9312
	v_cvt_pk_bf16_f32 v20, v23, s0
	ds_write_b16 v64, v16 offset:9344
	v_cvt_pk_bf16_f32 v16, v19, s0
	ds_write_b16 v64, v12 offset:13600
	v_cvt_pk_bf16_f32 v12, v15, s0
	ds_write_b16 v64, v8 offset:13632
	v_cvt_pk_bf16_f32 v8, v11, s0
	ds_write_b16 v64, v4 offset:13664
	v_cvt_pk_bf16_f32 v4, v7, s0
	ds_write_b16 v64, v0 offset:13696
	v_cvt_pk_bf16_f32 v0, v3, s0
	s_addc_u32 s3, s3, s4
	s_lshl_b32 s0, s0, 7
	s_ashr_i32 s1, s0, 31
	s_lshl_b64 s[0:1], s[0:1], 1
	s_add_u32 s0, s2, s0
	s_addc_u32 s1, s3, s1
	ds_write_b16 v64, v0 offset:13968
	s_add_u32 s0, s0, 0x4000000
	v_mov_b32_e32 v0, v160
	s_movk_i32 s2, 0x800
	ds_write_b16 v64, v60 offset:816
	ds_write_b16 v64, v56 offset:848
	ds_write_b16 v64, v52 offset:880
	ds_write_b16 v64, v48 offset:912
	ds_write_b16 v64, v44 offset:5168
	ds_write_b16 v64, v40 offset:5200
	ds_write_b16 v64, v36 offset:5232
	ds_write_b16 v64, v32 offset:5264
	ds_write_b16 v64, v28 offset:9520
	ds_write_b16 v64, v24 offset:9552
	ds_write_b16 v64, v20 offset:9584
	ds_write_b16 v64, v16 offset:9616
	ds_write_b16 v64, v12 offset:13872
	ds_write_b16 v64, v8 offset:13904
	ds_write_b16 v64, v4 offset:13936
	s_waitcnt lgkmcnt(0)
	s_barrier
	s_addc_u32 s1, s1, 0
	s_nop 0
	v_cmp_gt_i32_e32 vcc, s2, v0
	s_and_saveexec_b64 s[2:3], vcc
	s_cbranch_execz .LBB0_663
	v_ashrrev_i32_e32 v1, 31, v0
	v_lshrrev_b32_e32 v1, 28, v1
	v_add_u32_e32 v1, v0, v1
	v_ashrrev_i32_e32 v6, 4, v1
	v_and_b32_e32 v1, -16, v1
	s_movk_i32 s4, 0x110
	v_sub_u32_e32 v1, v0, v1
	v_mul_lo_u32 v4, v6, s4
	v_lshlrev_b32_e32 v2, 3, v1
	v_lshl_add_u32 v1, v1, 4, v4
	v_mov_b64_e32 v[4:5], s[0:1]
	s_movk_i32 s4, 0x1600
	v_ashrrev_i32_e32 v3, 31, v2
	v_mad_i64_i32 v[4:5], s[4:5], v6, s4, v[4:5]
	v_lshl_add_u64 v[6:7], v[2:3], 1, v[4:5]
	ds_read_b128 v[2:5], v1
	s_waitcnt lgkmcnt(0)
	global_store_dwordx4 v[6:7], v[2:5], off sc1
.LBB0_663:
	s_or_b64 exec, exec, s[2:3]
	s_movk_i32 s2, 0x700
	v_cmp_gt_i32_e32 vcc, s2, v0
	s_and_saveexec_b64 s[2:3], vcc
	s_cbranch_execz .LBB0_665
	v_add_u32_e32 v1, 0x100, v0
	v_ashrrev_i32_e32 v2, 31, v1
	v_lshrrev_b32_e32 v2, 28, v2
	v_add_u32_e32 v2, v1, v2
	v_ashrrev_i32_e32 v6, 4, v2
	v_and_b32_e32 v2, -16, v2
	s_movk_i32 s4, 0x110
	v_sub_u32_e32 v1, v1, v2
	v_mul_lo_u32 v4, v6, s4
	v_lshlrev_b32_e32 v2, 3, v1
	v_lshl_add_u32 v1, v1, 4, v4
	v_mov_b64_e32 v[4:5], s[0:1]
	s_movk_i32 s4, 0x1600
	v_ashrrev_i32_e32 v3, 31, v2
	v_mad_i64_i32 v[4:5], s[4:5], v6, s4, v[4:5]
	v_lshl_add_u64 v[6:7], v[2:3], 1, v[4:5]
	ds_read_b128 v[2:5], v1
	s_waitcnt lgkmcnt(0)
	global_store_dwordx4 v[6:7], v[2:5], off sc1
; template <int NCOLS>
; DI void store_tile_bf16(const u16* sC, u16* gdst, long ld, int rows_valid) {
;     ...
; #pragma unroll
;   for (int q = 0; q < (128 * CPR) / 256; ++q) {
;     const int c = tid + 256 * q, row = c / CPR, ch = c % CPR;
;     if (row < rows_valid) *(uint4*)(gdst + (long)row * ld + ch * 8) = *(const uint4*)(sC + row * LS + ch * 8);
;   }
.LBB0_665:
	s_or_b64 exec, exec, s[2:3]
	s_movk_i32 s2, 0x600
	v_cmp_gt_i32_e32 vcc, s2, v0
	s_and_saveexec_b64 s[2:3], vcc
	s_cbranch_execz .LBB0_667
	v_add_u32_e32 v1, 0x200, v0
	v_ashrrev_i32_e32 v2, 31, v1
	v_lshrrev_b32_e32 v2, 28, v2
	v_add_u32_e32 v2, v1, v2
	v_ashrrev_i32_e32 v6, 4, v2
	v_and_b32_e32 v2, -16, v2
	s_movk_i32 s4, 0x110
	v_sub_u32_e32 v1, v1, v2
	v_mul_lo_u32 v4, v6, s4
	v_lshlrev_b32_e32 v2, 3, v1
	v_lshl_add_u32 v1, v1, 4, v4
	v_mov_b64_e32 v[4:5], s[0:1]
	s_movk_i32 s4, 0x1600
	v_ashrrev_i32_e32 v3, 31, v2
	v_mad_i64_i32 v[4:5], s[4:5], v6, s4, v[4:5]
	v_lshl_add_u64 v[6:7], v[2:3], 1, v[4:5]
	ds_read_b128 v[2:5], v1
	s_waitcnt lgkmcnt(0)
	global_store_dwordx4 v[6:7], v[2:5], off sc1
.LBB0_667:
	s_or_b64 exec, exec, s[2:3]
	s_movk_i32 s2, 0x500
	v_cmp_gt_i32_e32 vcc, s2, v0
	s_and_saveexec_b64 s[2:3], vcc
	s_cbranch_execz .LBB0_669
	v_add_u32_e32 v1, 0x300, v0
	v_ashrrev_i32_e32 v2, 31, v1
	v_lshrrev_b32_e32 v2, 28, v2
	v_add_u32_e32 v2, v1, v2
	v_ashrrev_i32_e32 v6, 4, v2
	v_and_b32_e32 v2, -16, v2
	s_movk_i32 s4, 0x110
	v_sub_u32_e32 v1, v1, v2
	v_mul_lo_u32 v4, v6, s4
	v_lshlrev_b32_e32 v2, 3, v1
	v_lshl_add_u32 v1, v1, 4, v4
	v_mov_b64_e32 v[4:5], s[0:1]
	s_movk_i32 s4, 0x1600
	v_ashrrev_i32_e32 v3, 31, v2
	v_mad_i64_i32 v[4:5], s[4:5], v6, s4, v[4:5]
	v_lshl_add_u64 v[6:7], v[2:3], 1, v[4:5]
	ds_read_b128 v[2:5], v1
	s_waitcnt lgkmcnt(0)
	global_store_dwordx4 v[6:7], v[2:5], off sc1
.LBB0_669:
	s_or_b64 exec, exec, s[2:3]
	s_movk_i32 s2, 0x400
	v_cmp_gt_i32_e32 vcc, s2, v0
	s_and_saveexec_b64 s[2:3], vcc
	s_cbranch_execz .LBB0_671
	v_add_u32_e32 v1, 0x400, v0
	v_ashrrev_i32_e32 v2, 31, v1
	v_lshrrev_b32_e32 v2, 28, v2
	v_add_u32_e32 v2, v1, v2
	v_ashrrev_i32_e32 v6, 4, v2
	v_and_b32_e32 v2, -16, v2
	s_movk_i32 s4, 0x110
	v_sub_u32_e32 v1, v1, v2
	v_mul_lo_u32 v4, v6, s4
	v_lshlrev_b32_e32 v2, 3, v1
	v_lshl_add_u32 v1, v1, 4, v4
	v_mov_b64_e32 v[4:5], s[0:1]
	s_movk_i32 s4, 0x1600
	v_ashrrev_i32_e32 v3, 31, v2
	v_mad_i64_i32 v[4:5], s[4:5], v6, s4, v[4:5]
	v_lshl_add_u64 v[6:7], v[2:3], 1, v[4:5]
	ds_read_b128 v[2:5], v1
	s_waitcnt lgkmcnt(0)
	global_store_dwordx4 v[6:7], v[2:5], off sc1
.LBB0_671:
	s_or_b64 exec, exec, s[2:3]
	s_movk_i32 s2, 0x300
	v_cmp_gt_i32_e32 vcc, s2, v0
	s_and_saveexec_b64 s[2:3], vcc
	s_cbranch_execz .LBB0_673
	v_add_u32_e32 v1, 0x500, v0
	v_ashrrev_i32_e32 v2, 31, v1
	v_lshrrev_b32_e32 v2, 28, v2
	v_add_u32_e32 v2, v1, v2
	v_ashrrev_i32_e32 v6, 4, v2
	v_and_b32_e32 v2, -16, v2
	s_movk_i32 s4, 0x110
	v_sub_u32_e32 v1, v1, v2
	v_mul_lo_u32 v4, v6, s4
	v_lshlrev_b32_e32 v2, 3, v1
	v_lshl_add_u32 v1, v1, 4, v4
	v_mov_b64_e32 v[4:5], s[0:1]
	s_movk_i32 s4, 0x1600
	v_ashrrev_i32_e32 v3, 31, v2
	v_mad_i64_i32 v[4:5], s[4:5], v6, s4, v[4:5]
	v_lshl_add_u64 v[6:7], v[2:3], 1, v[4:5]
	ds_read_b128 v[2:5], v1
	s_waitcnt lgkmcnt(0)
	global_store_dwordx4 v[6:7], v[2:5], off sc1
.LBB0_673:
	s_or_b64 exec, exec, s[2:3]
	s_movk_i32 s2, 0x200
	v_cmp_gt_i32_e32 vcc, s2, v0
	s_and_saveexec_b64 s[2:3], vcc
	s_cbranch_execz .LBB0_675
	v_add_u32_e32 v1, 0x600, v0
	v_ashrrev_i32_e32 v2, 31, v1
	v_lshrrev_b32_e32 v2, 28, v2
	v_add_u32_e32 v2, v1, v2
	v_ashrrev_i32_e32 v6, 4, v2
	v_and_b32_e32 v2, -16, v2
	s_movk_i32 s4, 0x110
	v_sub_u32_e32 v1, v1, v2
	v_mul_lo_u32 v4, v6, s4
	v_lshlrev_b32_e32 v2, 3, v1
	v_lshl_add_u32 v1, v1, 4, v4
	v_mov_b64_e32 v[4:5], s[0:1]
	s_movk_i32 s4, 0x1600
	v_ashrrev_i32_e32 v3, 31, v2
	v_mad_i64_i32 v[4:5], s[4:5], v6, s4, v[4:5]
	v_lshl_add_u64 v[6:7], v[2:3], 1, v[4:5]
	ds_read_b128 v[2:5], v1
	s_waitcnt lgkmcnt(0)
	global_store_dwordx4 v[6:7], v[2:5], off sc1
.LBB0_675:
	s_or_b64 exec, exec, s[2:3]
	s_movk_i32 s2, 0x100
	v_cmp_gt_i32_e32 vcc, s2, v0
	s_and_saveexec_b64 s[2:3], vcc
	s_cbranch_execz .LBB0_658
	v_add_u32_e32 v0, 0x700, v0
	v_ashrrev_i32_e32 v1, 31, v0
	v_lshrrev_b32_e32 v1, 28, v1
	v_add_u32_e32 v1, v0, v1
	v_ashrrev_i32_e32 v4, 4, v1
	v_and_b32_e32 v1, -16, v1
	s_movk_i32 s4, 0x110
	v_sub_u32_e32 v2, v0, v1
	v_mul_lo_u32 v3, v4, s4
	v_lshlrev_b32_e32 v0, 3, v2
	v_lshl_add_u32 v6, v2, 4, v3
	v_mov_b64_e32 v[2:3], s[0:1]
	s_movk_i32 s0, 0x1600
	v_ashrrev_i32_e32 v1, 31, v0
	v_mad_i64_i32 v[2:3], s[0:1], v4, s0, v[2:3]
	v_lshl_add_u64 v[4:5], v[0:1], 1, v[2:3]
	ds_read_b128 v[0:3], v6
	s_waitcnt lgkmcnt(0)
	global_store_dwordx4 v[4:5], v[0:3], off sc1
	s_branch .LBB0_658

; DI unsigned pk2(float a, float b) { f32x2_t v = {a, b}; bf16x2_t r = __builtin_convertvector(v, bf16x2_t); return __builtin_bit_cast(unsigned, r); }
; DI void phase_rmsnorm(const float* __restrict__ x, const float* __restrict__ wgt, u16* __restrict__ H) {
;     ...
;   for (int row = gw; row < T_; row += nw) {
;     const float4* xr = (const float4*)(x + (long)row * DM);
;     float4 v[4]; float s = 0.f;
; #pragma unroll
;     for (int j = 0; j < 4; ++j) { v[j] = xr[lane + 64 * j]; s += v[j].x * v[j].x + v[j].y * v[j].y + v[j].z * v[j].z + v[j].w * v[j].w; }
;     s = wave_sum(s);
;     float r = rsqrtf(s * (1.f / DM) + EPS);
; #pragma unroll
;     for (int j = 0; j < 4; ++j) {
;       float4 g = ((const float4*)wgt)[lane + 64 * j];
;       uint2 o; o.x = pk2(v[j].x * r * g.x, v[j].y * r * g.y); o.y = pk2(v[j].z * r * g.z, v[j].w * r * g.w);
;       *(uint2*)(H + (long)row * DM + (lane + 64 * j) * 4) = o;
;     }
;   }
.LBB0_682:
	global_load_dwordx4 v[28:31], v[20:21], off nt
	global_load_dwordx4 v[32:35], v[20:21], off offset:1024 nt
	v_add_u32_e32 v16, s40, v16
	s_waitcnt vmcnt(1)
	v_mov_b32_e32 v42, v29
	s_waitcnt vmcnt(0)
	v_mov_b32_e32 v43, v33
	v_mov_b32_e32 v40, v28
	v_mov_b32_e32 v41, v32
	v_pk_mul_f32 v[42:43], v[42:43], v[42:43]
	v_mov_b32_e32 v36, v30
	v_mov_b32_e32 v37, v34
	v_pk_fma_f32 v[40:41], v[40:41], v[40:41], v[42:43]
	v_mov_b32_e32 v38, v31
	v_mov_b32_e32 v39, v35
	v_pk_fma_f32 v[36:37], v[36:37], v[36:37], v[40:41]
	s_nop 0
	v_pk_fma_f32 v[44:45], v[38:39], v[38:39], v[36:37]
	global_load_dwordx4 v[36:39], v[20:21], off offset:2048 nt
	global_load_dwordx4 v[40:43], v[20:21], off offset:3072 nt
	v_add_f32_e32 v17, v44, v45
	v_lshl_add_u64 v[20:21], v[20:21], 0, s[24:25]
	s_waitcnt vmcnt(1)
	v_mov_b32_e32 v52, v37
	s_waitcnt vmcnt(0)
	v_mov_b32_e32 v53, v41
	v_mov_b32_e32 v50, v36
	v_mov_b32_e32 v51, v40
	v_pk_mul_f32 v[52:53], v[52:53], v[52:53]
	v_mov_b32_e32 v46, v38
	v_mov_b32_e32 v47, v42
	v_pk_fma_f32 v[50:51], v[50:51], v[50:51], v[52:53]
	v_mov_b32_e32 v48, v39
	v_mov_b32_e32 v49, v43
	v_pk_fma_f32 v[46:47], v[46:47], v[46:47], v[50:51]
	s_nop 0
	v_pk_fma_f32 v[46:47], v[48:49], v[48:49], v[46:47]
	s_nop 0
	v_add_f32_e32 v17, v17, v46
	v_add_f32_e32 v17, v17, v47
	ds_bpermute_b32 v44, v22, v17
	s_waitcnt lgkmcnt(0)
	v_add_f32_e32 v17, v17, v44
	ds_bpermute_b32 v44, v23, v17
	s_waitcnt lgkmcnt(0)
	v_add_f32_e32 v17, v17, v44
	ds_bpermute_b32 v44, v24, v17
	s_waitcnt lgkmcnt(0)
	v_add_f32_e32 v17, v17, v44
	ds_bpermute_b32 v44, v25, v17
	s_waitcnt lgkmcnt(0)
	v_add_f32_e32 v17, v17, v44
	ds_bpermute_b32 v44, v26, v17
	s_waitcnt lgkmcnt(0)
	v_add_f32_e32 v17, v17, v44
	ds_bpermute_b32 v44, v27, v17
	s_waitcnt lgkmcnt(0)
	v_add_f32_e32 v17, v17, v44
	v_fmamk_f32 v17, v17, 0x3a800000, v164
	v_cmp_gt_f32_e32 vcc, s26, v17
	v_mul_f32_e32 v44, 0x4b800000, v17
	s_nop 0
	v_cndmask_b32_e32 v17, v17, v44, vcc
	v_rsq_f32_e32 v17, v17
	s_nop 0
	v_mul_f32_e32 v44, 0x45800000, v17
	v_cndmask_b32_e32 v44, v17, v44, vcc
	v_pk_mul_f32 v[28:29], v[28:29], v[44:45] op_sel_hi:[1,0]
	v_pk_mul_f32 v[30:31], v[30:31], v[44:45] op_sel_hi:[1,0]
	v_pk_mul_f32 v[28:29], v[0:1], v[28:29]
	v_pk_mul_f32 v[30:31], v[2:3], v[30:31]
	v_cvt_pk_bf16_f32 v28, v28, v29
	v_cvt_pk_bf16_f32 v29, v30, v31
	global_store_dwordx2 v[18:19], v[28:29], off offset:-1024 sc1
	v_pk_mul_f32 v[28:29], v[32:33], v[44:45] op_sel_hi:[1,0]
	v_pk_mul_f32 v[30:31], v[34:35], v[44:45] op_sel_hi:[1,0]
	v_pk_mul_f32 v[28:29], v[4:5], v[28:29]
	v_pk_mul_f32 v[30:31], v[6:7], v[30:31]
	v_cvt_pk_bf16_f32 v28, v28, v29
	v_cvt_pk_bf16_f32 v29, v30, v31
	global_store_dwordx2 v[18:19], v[28:29], off offset:-512 sc1
	v_pk_mul_f32 v[28:29], v[36:37], v[44:45] op_sel_hi:[1,0]
	v_pk_mul_f32 v[30:31], v[38:39], v[44:45] op_sel_hi:[1,0]
	v_pk_mul_f32 v[28:29], v[8:9], v[28:29]
	v_pk_mul_f32 v[30:31], v[10:11], v[30:31]
	v_cvt_pk_bf16_f32 v28, v28, v29
	v_cvt_pk_bf16_f32 v29, v30, v31
	global_store_dwordx2 v[18:19], v[28:29], off sc1
	v_pk_mul_f32 v[28:29], v[40:41], v[44:45] op_sel_hi:[1,0]
	v_pk_mul_f32 v[30:31], v[42:43], v[44:45] op_sel_hi:[1,0]
	v_pk_mul_f32 v[28:29], v[12:13], v[28:29]
	v_pk_mul_f32 v[30:31], v[14:15], v[30:31]
	v_cvt_pk_bf16_f32 v28, v28, v29
	v_cvt_pk_bf16_f32 v29, v30, v31
	v_cmp_lt_i32_e32 vcc, s27, v16
	global_store_dwordx2 v[18:19], v[28:29], off offset:512 sc1
	v_lshl_add_u64 v[18:19], v[18:19], 0, s[6:7]
	s_or_b64 s[2:3], vcc, s[2:3]
	s_andn2_b64 exec, exec, s[2:3]
	s_cbranch_execnz .LBB0_682

; DI void phase_convert(const Params& P, int l, float* lds) {
;     ...
;   for (int it = blockIdx.x; it < 4648; it += gridDim.x) {
;     int r = it, mat = 0, nbk = 0, kbk = 0; size_t off = 0;
; #pragma unroll
;     for (int q = 0; q < 9; ++q) { int n = NB_[q] * KB_[q]; if (r >= 0 && r < n) { mat = q; nbk = NB_[q]; kbk = KB_[q]; off = OFF_[q]; r -= 100000; } else if (r >= 0) r -= n; }
;     r += 100000;
;     const int nb = r / kbk, kb = r % kbk, K = kbk * 64;
;     (void)nbk;
;     __syncthreads();
;     {
;       const int n = tid & 63;
;       long ld; const float* cp = conv_colptr(P, l, mat, nb * 64 + n, ld);
; #pragma unroll 4
;       for (int q = 0; q < 16; ++q) { int k = (tid >> 6) + 4 * q; lds[n * 65 + k] = cp[(long)(kb * 64 + k) * ld]; }
;     }
.LBB0_753:
	s_mul_i32 s23, s23, s19
	s_sub_i32 s16, s22, s23
	s_lshl_b32 s16, s16, 6
	s_mov_b32 s17, s14
	s_mov_b32 s21, s15
	s_mov_b32 s22, s16
	s_mov_b32 s23, 1
	s_mov_b32 s24, 0
	s_mov_b32 s25, 16
	s_movk_i32 s26, 4
	s_movk_i32 s27, 0
	v_add_u32_e32 v26, s26, v1
	v_add_u32_e32 v23, s27, v2
	v_add_u32_e32 v16, s22, v26
	v_add_u32_e32 v24, s16, v23
	v_ashrrev_i32_e32 v17, 31, v16
	v_ashrrev_i32_e32 v25, 31, v24
	v_mul_lo_u32 v27, s17, v17
	v_mul_lo_u32 v28, s21, v16
	v_mad_u64_u32 v[16:17], s[28:29], s17, v16, 0
	v_add3_u32 v17, v17, v27, v28
	v_mul_lo_u32 v27, s14, v25
	v_mul_lo_u32 v28, s15, v24
	v_mad_u64_u32 v[24:25], s[28:29], s14, v24, 0
	v_add3_u32 v25, v25, v27, v28
	v_lshl_add_u64 v[24:25], v[24:25], 2, v[14:15]
	v_lshl_add_u64 v[16:17], v[16:17], 2, v[14:15]
	global_load_dword v30, v[24:25], off nt
	global_load_dword v31, v[16:17], off nt
	v_lshl_add_u32 v46, v23, 2, v18
	v_lshl_add_u32 v47, v26, 2, v18
	v_add_u32_e32 v26, s26, v3
	v_add_u32_e32 v23, s27, v8
	v_add_u32_e32 v16, s22, v26
	v_add_u32_e32 v24, s16, v23
	v_ashrrev_i32_e32 v17, 31, v16
	v_ashrrev_i32_e32 v25, 31, v24
	v_mul_lo_u32 v27, s17, v17
	v_mul_lo_u32 v28, s21, v16
	v_mad_u64_u32 v[16:17], s[28:29], s17, v16, 0
	v_add3_u32 v17, v17, v27, v28
	v_mul_lo_u32 v27, s14, v25
	v_mul_lo_u32 v28, s15, v24
	v_mad_u64_u32 v[24:25], s[28:29], s14, v24, 0
	v_add3_u32 v25, v25, v27, v28
	v_lshl_add_u64 v[24:25], v[24:25], 2, v[14:15]
	v_lshl_add_u64 v[16:17], v[16:17], 2, v[14:15]
	global_load_dword v32, v[24:25], off nt
	global_load_dword v33, v[16:17], off nt
	v_lshl_add_u32 v48, v23, 2, v18
	v_lshl_add_u32 v49, v26, 2, v18
	v_add_u32_e32 v26, s26, v9
	v_add_u32_e32 v23, s27, v10
	v_add_u32_e32 v16, s22, v26
	v_add_u32_e32 v24, s16, v23
	v_ashrrev_i32_e32 v17, 31, v16
	v_ashrrev_i32_e32 v25, 31, v24
	v_mul_lo_u32 v27, s17, v17
	v_mul_lo_u32 v28, s21, v16
	v_mad_u64_u32 v[16:17], s[28:29], s17, v16, 0
	v_add3_u32 v17, v17, v27, v28
	v_mul_lo_u32 v27, s14, v25
	v_mul_lo_u32 v28, s15, v24
	v_mad_u64_u32 v[24:25], s[28:29], s14, v24, 0
	v_add3_u32 v25, v25, v27, v28
	v_lshl_add_u64 v[24:25], v[24:25], 2, v[14:15]
	v_lshl_add_u64 v[16:17], v[16:17], 2, v[14:15]
	global_load_dword v34, v[24:25], off nt
	global_load_dword v35, v[16:17], off nt
	v_lshl_add_u32 v50, v23, 2, v18
	v_lshl_add_u32 v51, v26, 2, v18
	v_add_u32_e32 v26, s26, v11
	v_add_u32_e32 v23, s27, v12
	v_add_u32_e32 v16, s22, v26
	v_add_u32_e32 v24, s16, v23
	v_ashrrev_i32_e32 v17, 31, v16
	v_ashrrev_i32_e32 v25, 31, v24
	v_mul_lo_u32 v27, s17, v17
	v_mul_lo_u32 v28, s21, v16
	v_mad_u64_u32 v[16:17], s[28:29], s17, v16, 0
	v_add3_u32 v17, v17, v27, v28
	v_mul_lo_u32 v27, s14, v25
	v_mul_lo_u32 v28, s15, v24
	v_mad_u64_u32 v[24:25], s[28:29], s14, v24, 0
	v_add3_u32 v25, v25, v27, v28
	v_lshl_add_u64 v[24:25], v[24:25], 2, v[14:15]
	v_lshl_add_u64 v[16:17], v[16:17], 2, v[14:15]
	global_load_dword v36, v[24:25], off nt
	global_load_dword v37, v[16:17], off nt
	v_lshl_add_u32 v52, v23, 2, v18
	v_lshl_add_u32 v53, v26, 2, v18
	s_movk_i32 s26, 36
	s_movk_i32 s27, 32
	v_add_u32_e32 v26, s26, v1
	v_add_u32_e32 v23, s27, v2
	v_add_u32_e32 v16, s22, v26
	v_add_u32_e32 v24, s16, v23
	v_ashrrev_i32_e32 v17, 31, v16
	v_ashrrev_i32_e32 v25, 31, v24
	v_mul_lo_u32 v27, s17, v17
	v_mul_lo_u32 v28, s21, v16
	v_mad_u64_u32 v[16:17], s[28:29], s17, v16, 0
	v_add3_u32 v17, v17, v27, v28
	v_mul_lo_u32 v27, s14, v25
	v_mul_lo_u32 v28, s15, v24
	v_mad_u64_u32 v[24:25], s[28:29], s14, v24, 0
	v_add3_u32 v25, v25, v27, v28
	v_lshl_add_u64 v[24:25], v[24:25], 2, v[14:15]
	v_lshl_add_u64 v[16:17], v[16:17], 2, v[14:15]
	global_load_dword v38, v[24:25], off nt
	global_load_dword v39, v[16:17], off nt
	v_lshl_add_u32 v54, v23, 2, v18
	v_lshl_add_u32 v55, v26, 2, v18
	v_add_u32_e32 v26, s26, v3
	v_add_u32_e32 v23, s27, v8
	v_add_u32_e32 v16, s22, v26
	v_add_u32_e32 v24, s16, v23
	v_ashrrev_i32_e32 v17, 31, v16
	v_ashrrev_i32_e32 v25, 31, v24
	v_mul_lo_u32 v27, s17, v17
	v_mul_lo_u32 v28, s21, v16
	v_mad_u64_u32 v[16:17], s[28:29], s17, v16, 0
	v_add3_u32 v17, v17, v27, v28
	v_mul_lo_u32 v27, s14, v25
	v_mul_lo_u32 v28, s15, v24
	v_mad_u64_u32 v[24:25], s[28:29], s14, v24, 0
	v_add3_u32 v25, v25, v27, v28
	v_lshl_add_u64 v[24:25], v[24:25], 2, v[14:15]
	v_lshl_add_u64 v[16:17], v[16:17], 2, v[14:15]
	global_load_dword v40, v[24:25], off nt
	global_load_dword v41, v[16:17], off nt
	v_lshl_add_u32 v56, v23, 2, v18
	v_lshl_add_u32 v57, v26, 2, v18
	v_add_u32_e32 v26, s26, v9
	v_add_u32_e32 v23, s27, v10
	v_add_u32_e32 v16, s22, v26
	v_add_u32_e32 v24, s16, v23
	v_ashrrev_i32_e32 v17, 31, v16
	v_ashrrev_i32_e32 v25, 31, v24
	v_mul_lo_u32 v27, s17, v17
	v_mul_lo_u32 v28, s21, v16
	v_mad_u64_u32 v[16:17], s[28:29], s17, v16, 0
	v_add3_u32 v17, v17, v27, v28
	v_mul_lo_u32 v27, s14, v25
	v_mul_lo_u32 v28, s15, v24
	v_mad_u64_u32 v[24:25], s[28:29], s14, v24, 0
	v_add3_u32 v25, v25, v27, v28
	v_lshl_add_u64 v[24:25], v[24:25], 2, v[14:15]
	v_lshl_add_u64 v[16:17], v[16:17], 2, v[14:15]
	global_load_dword v42, v[24:25], off nt
	global_load_dword v43, v[16:17], off nt
	v_lshl_add_u32 v58, v23, 2, v18
	v_lshl_add_u32 v59, v26, 2, v18
	v_add_u32_e32 v26, s26, v11
	v_add_u32_e32 v23, s27, v12
	v_add_u32_e32 v16, s22, v26
	v_add_u32_e32 v24, s16, v23
	v_ashrrev_i32_e32 v17, 31, v16
	v_ashrrev_i32_e32 v25, 31, v24
	v_mul_lo_u32 v27, s17, v17
	v_mul_lo_u32 v28, s21, v16
	v_mad_u64_u32 v[16:17], s[28:29], s17, v16, 0
	v_add3_u32 v17, v17, v27, v28
	v_mul_lo_u32 v27, s14, v25
	v_mul_lo_u32 v28, s15, v24
	v_mad_u64_u32 v[24:25], s[28:29], s14, v24, 0
	v_add3_u32 v25, v25, v27, v28
	v_lshl_add_u64 v[24:25], v[24:25], 2, v[14:15]
	v_lshl_add_u64 v[16:17], v[16:17], 2, v[14:15]
	global_load_dword v44, v[24:25], off nt
	global_load_dword v45, v[16:17], off nt
	v_lshl_add_u32 v60, v23, 2, v18
	v_lshl_add_u32 v61, v26, 2, v18
	s_mov_b32 s23, 17
	s_mov_b32 s24, 16
	s_mov_b32 s25, 0
	s_waitcnt vmcnt(0)
	ds_write_b32 v46, v30
	ds_write_b32 v47, v31
	ds_write_b32 v48, v32
	ds_write_b32 v49, v33
	ds_write_b32 v50, v34
	ds_write_b32 v51, v35
	ds_write_b32 v52, v36
	ds_write_b32 v53, v37
	ds_write_b32 v54, v38
	ds_write_b32 v55, v39
	ds_write_b32 v56, v40
	ds_write_b32 v57, v41
	ds_write_b32 v58, v42
	ds_write_b32 v59, v43
	ds_write_b32 v60, v44
	ds_write_b32 v61, v45
	s_mov_b64 s[14:15], 0
	s_lshl_b32 s19, s19, 6
	s_waitcnt lgkmcnt(0)
	s_barrier
; DI unsigned char* WSP(const Params& P) { size_t z = 0; asm volatile("" : "+s"(z)); return P.ws + z; }
; DI unsigned pk2(float a, float b) { f32x2_t v = {a, b}; bf16x2_t r = __builtin_convertvector(v, bf16x2_t); return __builtin_bit_cast(unsigned, r); }
; DI void phase_convert(const Params& P, int l, float* lds) {
;     ...
;     __syncthreads();
;     u16* dst = (u16*)(WSP(P) + WS_W + off);
; #pragma unroll
;     for (int q = 0; q < 2; ++q) {
;       int c = tid + 256 * q, n = c >> 3, k8 = (c & 7) * 8;
;       const float* sp = lds + n * 65 + k8;
;       uint4 v; v.x = pk2(sp[0], sp[1]); v.y = pk2(sp[2], sp[3]); v.z = pk2(sp[4], sp[5]); v.w = pk2(sp[6], sp[7]);
;       *(uint4*)(dst + (long)(nb * 64 + n) * K + kb * 64 + k8) = v;
;     }
	s_add_u32 s14, s70, s14
	s_addc_u32 s15, s71, s15
	s_add_u32 s14, s14, s44
	s_addc_u32 s15, s15, s45
	s_ashr_i32 s17, s16, 31
	s_lshl_b64 s[12:13], s[16:17], 1
	s_add_u32 s12, s14, s12
	s_addc_u32 s13, s15, s13
	v_lshl_add_u64 v[14:15], s[12:13], 0, v[162:163]
	s_mov_b64 s[12:13], 0x1d100000
	v_lshl_add_u64 v[24:25], v[14:15], 0, s[12:13]
	ds_read2_b32 v[14:15], v21 offset1:1
	ds_read2_b32 v[16:17], v21 offset0:2 offset1:3
	ds_read2_b32 v[26:27], v21 offset0:6 offset1:7
	v_add_u32_e32 v23, s20, v19
	s_waitcnt lgkmcnt(2)
	v_cvt_pk_bf16_f32 v14, v14, v15
	s_waitcnt lgkmcnt(1)
	v_cvt_pk_bf16_f32 v15, v16, v17
	ds_read2_b32 v[16:17], v21 offset0:4 offset1:5
	s_waitcnt lgkmcnt(0)
	v_cvt_pk_bf16_f32 v16, v16, v17
	v_cvt_pk_bf16_f32 v17, v26, v27
	v_mad_i64_i32 v[26:27], s[12:13], v23, s19, 0
	v_lshl_add_u64 v[26:27], v[26:27], 1, v[24:25]
	global_store_dwordx4 v[26:27], v[14:17], off sc1
	ds_read2_b32 v[14:15], v22 offset1:1
	ds_read2_b32 v[16:17], v22 offset0:2 offset1:3
	ds_read2_b32 v[26:27], v22 offset0:6 offset1:7
	v_add_u32_e32 v23, s20, v20
	s_waitcnt lgkmcnt(2)
	v_cvt_pk_bf16_f32 v14, v14, v15
	s_waitcnt lgkmcnt(1)
	v_cvt_pk_bf16_f32 v15, v16, v17
	ds_read2_b32 v[16:17], v22 offset0:4 offset1:5
	s_waitcnt lgkmcnt(0)
	v_cvt_pk_bf16_f32 v16, v16, v17
	v_cvt_pk_bf16_f32 v17, v26, v27
	v_mad_i64_i32 v[26:27], s[12:13], v23, s19, 0
	v_readlane_b32 s12, v247, 3
	s_add_i32 s18, s18, s12
	v_lshl_add_u64 v[24:25], v[26:27], 1, v[24:25]
	s_cmpk_lt_i32 s18, 0x1228
	global_store_dwordx4 v[24:25], v[14:17], off sc1
	s_cbranch_scc1 .LBB0_689
	s_branch .LBB0_768
